# attention K/V staging via LDS-DMA (global_load_lds_dwordx4, source-side swizzle) instead of global_load+ds_write_b128; DMA issued right after each wave's barrier, vmcnt(0) before the next
# speedup vs baseline: 1.0694x; 1.0141x over previous
; __device__ __forceinline__ int lane_id_asm() { int r; asm volatile("v_mbcnt_lo_u32_b32 %0, -1, 0\n\tv_mbcnt_hi_u32_b32 %0, -1, %0" : "=v"(r)); return r; }
; __device__ __forceinline__ void attn_item(const bf16_t* __restrict__ Qb, const bf16_t* __restrict__ Kh, const bf16_t* __restrict__ Vh, const bf16_t* __restrict__ Zb, ...
;   int tid_ = MYTID(wid_s); asm volatile("" : "+v"(tid_)); const int tid = tid_, wid = tid >> 6, lane = tid & 63, r32 = lane & 31, hi = lane >> 5;
;   constexpr int SLOT = 32768, KOFF = 16384, WSOFF = 3 * SLOT;
;   float* ws = (float*)(lds + WSOFF) + wid * 64; float* al_l = ws + 32;
;   float m_reg = 0.f, l_reg = 0; f32x16 o[4] = {}; bf16x8 qr[8]; f32x16 negm = f32x16{}; asm volatile("" : "+v"(negm));
;   const bf16_t* Qw = Qb + (long)(wid * QBLK + r32) * LDQ + hi * 8;
;   float qn2 = 0.f;
;   {
;     u32x4 qw[8];
; #pragma unroll
;     for (int d0 = 0; d0 < 8; ++d0) qw[d0] = *reinterpret_cast<const u32x4*>(Qw + d0 * 16);
;     float ss = 0.f;
; #pragma unroll
;     for (int d0 = 0; d0 < 8; ++d0) { const float a0 = bflo(qw[d0].x), a1 = bfhi(qw[d0].x), a2 = bflo(qw[d0].y), a3 = bfhi(qw[d0].y), a4 = bflo(qw[d0].z), a5 = bfhi(qw[d0].z), a6 = bflo(qw[d0].w), a7 = bfhi(qw[d0].w);
;       ss += (a0 * a0 + a1 * a1) + (a2 * a2 + a3 * a3) + (a4 * a4 + a5 * a5) + (a6 * a6 + a7 * a7); }
;     { auto rr = __builtin_amdgcn_permlane32_swap(__float_as_uint(ss), __float_as_uint(ss), false, false); ss = __uint_as_float(rr[0]) + __uint_as_float(rr[1]); }
;     const float rstd = __builtin_amdgcn_rsqf(ss * (1.0f / 128.0f) + NORM_EPS) * (SCALE * 1.4426950408889634f);
;     const int hq = lane_id_asm() >> 5;
;     const int spos = qpos0 + wid * QBLK + r32; const float prow = (float)(spos >> 6), pcol = (float)(spos & 63);
; #pragma unroll
;     for (int bb = 0; bb < 4; ++bb) { const int d1 = (bb & 1) + 4 * (bb >> 1), d2 = d1 + 2;
;       const float pos = (bb < 2) ? prow : pcol; const float* g1p = qg + d1 * 16 + hq * 8; const float* g2p = qg + d2 * 16 + hq * 8;
;       const f32x4 g1a = *(const f32x4*)g1p, g1b = *(const f32x4*)(g1p + 4), g2a = *(const f32x4*)g2p, g2b = *(const f32x4*)(g2p + 4);
;       float o1[8], o2[8];
; #pragma unroll
;       for (int e = 0; e < 8; ++e) { const unsigned w1 = (e < 2) ? qw[d1].x : (e < 4) ? qw[d1].y : (e < 6) ? qw[d1].z : qw[d1].w, w2 = (e < 2) ? qw[d2].x : (e < 4) ? qw[d2].y : (e < 6) ? qw[d2].z : qw[d2].w;
.LBB0_452:
	s_lshl_b32 s0, s70, 5
	s_and_b32 s0, s0, 32
	s_bfe_u32 s7, s70, 0x50003
	s_or_b32 s7, s0, s7
	s_lshl_b32 s0, s70, 12
	s_and_b32 s0, s0, 0x4000
	s_lshl_b32 s7, s7, 8
	s_bfe_u32 s1, s70, 0x10001
	s_or_b32 s71, s7, s0
	s_bfe_u32 s6, s54, 0x1000e
	s_lshl_b32 s8, s1, 8
	s_mul_i32 s9, s71, 0x2080
	s_add_u32 s9, s42, s9
	s_addc_u32 s36, s43, 0
	s_ashr_i32 s24, s70, 1
	s_lshl_b32 s1, s1, 9
	s_and_b32 s24, s24, 0xffffff80
	s_add_i32 s24, s1, s24
	s_ashr_i32 s25, s24, 31
	s_lshl_b64 s[26:27], s[24:25], 1
	s_add_u32 s24, s9, s26
	v_mbcnt_lo_u32_b32 v0, -1, 0
	v_mbcnt_hi_u32_b32 v0, -1, v0
	s_addc_u32 s25, s36, s27
	v_add_u32_e32 v186, s33, v0
	v_mov_b64_e32 v[2:3], s[24:25]
	v_ashrrev_i32_e32 v0, 1, v186
	v_and_b32_e32 v4, 0xffffffe0, v0
	v_bfi_b32 v0, s57, v0, v186
	v_lshrrev_b32_e32 v188, 1, v186
	v_mad_i64_i32 v[2:3], s[36:37], v0, s51, v[2:3]
	v_and_b32_e32 v212, 16, v188
	v_mov_b32_e32 v213, v1
	v_mov_b32_e32 v16, v1
	v_mov_b32_e32 v17, v1
	v_mov_b32_e32 v18, v1
	v_mov_b32_e32 v19, v1
	v_mov_b32_e32 v20, v1
	v_mov_b32_e32 v21, v1
	v_mov_b32_e32 v22, v1
	v_mov_b32_e32 v23, v1
	v_mov_b32_e32 v24, v1
	v_mov_b32_e32 v25, v1
	v_mov_b32_e32 v26, v1
	v_mov_b32_e32 v27, v1
	v_mov_b32_e32 v28, v1
	v_mov_b32_e32 v29, v1
	v_mov_b32_e32 v30, v1
	v_mov_b32_e32 v31, v1
	v_lshl_add_u64 v[2:3], v[2:3], 0, v[212:213]
	global_load_dwordx4 v[36:39], v[2:3], off
	global_load_dwordx4 v[44:47], v[2:3], off offset:32
	global_load_dwordx4 v[40:43], v[2:3], off offset:64
	global_load_dwordx4 v[48:51], v[2:3], off offset:96
	global_load_dwordx4 v[52:55], v[2:3], off offset:128
	global_load_dwordx4 v[60:63], v[2:3], off offset:160
	global_load_dwordx4 v[56:59], v[2:3], off offset:192
	global_load_dwordx4 v[64:67], v[2:3], off offset:224
	v_mbcnt_lo_u32_b32 v0, -1, 0
	v_mbcnt_hi_u32_b32 v0, -1, v0
	v_and_b32_e32 v187, 31, v186
	v_ashrrev_i32_e32 v0, 2, v0
	v_and_b32_e32 v78, -8, v0
	v_or_b32_e32 v69, 1, v78
	v_cvt_f32_i32_e32 v69, v69
	v_cvt_f32_i32_e32 v6, v78
	v_or_b32_e32 v2, s7, v187
	s_waitcnt vmcnt(22)
	v_add_u32_e32 v136, v2, v4
	v_mul_f32_e32 v69, 0xbed49a78, v69
	v_exp_f32_e32 v69, v69
	v_mul_f32_e32 v6, 0xbed49a78, v6
	v_ashrrev_i32_e32 v2, 6, v136
	v_exp_f32_e32 v68, v6
	v_mul_f32_e32 v138, 0.15915494, v69
	v_or_b32_e32 v69, 2, v78
	s_waitcnt vmcnt(20)
	v_cvt_f32_i32_e32 v145, v2
	v_cvt_f32_i32_e32 v69, v69
	v_ashrrev_i32_e32 v79, 31, v78
	v_lshl_add_u64 v[14:15], v[78:79], 2, s[18:19]
	global_load_dwordx4 v[10:13], v[14:15], off
	global_load_dwordx4 v[2:5], v[14:15], off offset:16
	global_load_dwordx4 v[32:35], v[14:15], off offset:128
	global_load_dwordx4 v[6:9], v[14:15], off offset:144
	v_mul_f32_e32 v137, 0.15915494, v68
	v_mul_f32_e32 v68, v137, v145
	v_mul_f32_e32 v69, 0xbed49a78, v69
	v_floor_f32_e32 v68, v68
	v_exp_f32_e32 v69, v69
	v_fma_f32 v68, v137, v145, -v68
	v_sin_f32_e32 v104, v68
	v_cos_f32_e32 v105, v68
	v_mul_f32_e32 v68, v138, v145
	v_floor_f32_e32 v68, v68
	v_fma_f32 v68, v138, v145, -v68
	v_mul_f32_e32 v139, 0.15915494, v69
	v_sin_f32_e32 v83, v68
	v_cos_f32_e32 v82, v68
	v_or_b32_e32 v68, 3, v78
	v_mul_f32_e32 v69, v139, v145
	v_cvt_f32_i32_e32 v68, v68
	v_floor_f32_e32 v69, v69
	v_fma_f32 v69, v139, v145, -v69
	v_sin_f32_e32 v106, v69
	v_cos_f32_e32 v107, v69
	v_or_b32_e32 v69, 4, v78
	v_cvt_f32_i32_e32 v69, v69
	v_mul_f32_e32 v68, 0xbed49a78, v68
	v_exp_f32_e32 v68, v68
	v_or_b32_e32 v0, 7, v0
	v_mul_f32_e32 v69, 0xbed49a78, v69
	v_exp_f32_e32 v69, v69
	v_mul_f32_e32 v140, 0.15915494, v68
	v_mul_f32_e32 v68, v140, v145
	v_floor_f32_e32 v68, v68
	v_fma_f32 v68, v140, v145, -v68
	v_mul_f32_e32 v141, 0.15915494, v69
	v_sin_f32_e32 v97, v68
	v_cos_f32_e32 v96, v68
	v_or_b32_e32 v68, 5, v78
	v_mul_f32_e32 v69, v141, v145
	v_cvt_f32_i32_e32 v68, v68
	v_floor_f32_e32 v69, v69
	v_fma_f32 v69, v141, v145, -v69
	v_sin_f32_e32 v108, v69
	v_cos_f32_e32 v109, v69
	v_or_b32_e32 v69, 6, v78
	v_cvt_f32_i32_e32 v69, v69
	v_mul_f32_e32 v68, 0xbed49a78, v68
	v_exp_f32_e32 v68, v68
	v_cvt_f32_i32_e32 v0, v0
	v_mul_f32_e32 v69, 0xbed49a78, v69
	v_exp_f32_e32 v69, v69
	v_mul_f32_e32 v142, 0.15915494, v68
	v_mul_f32_e32 v68, v142, v145
	v_floor_f32_e32 v68, v68
	v_fma_f32 v68, v142, v145, -v68
	v_mul_f32_e32 v143, 0.15915494, v69
	v_mul_f32_e32 v0, 0xbed49a78, v0
	v_sin_f32_e32 v101, v68
	v_cos_f32_e32 v100, v68
	v_mul_f32_e32 v68, v143, v145
	v_exp_f32_e32 v0, v0
	v_floor_f32_e32 v68, v68
	v_fma_f32 v68, v143, v145, -v68
	v_sin_f32_e32 v110, v68
	v_cos_f32_e32 v111, v68
	v_add_u32_e32 v68, 16, v78
	v_mul_f32_e32 v144, 0.15915494, v0
	v_cvt_f32_i32_e32 v68, v68
	v_mul_f32_e32 v0, v144, v145
	v_floor_f32_e32 v0, v0
	v_fma_f32 v0, v144, v145, -v0
	v_sin_f32_e32 v99, v0
	v_cos_f32_e32 v98, v0
	v_mul_f32_e32 v0, 0xbed49a78, v68
	s_waitcnt vmcnt(5)
; __device__ __forceinline__ float bflo(unsigned w) { return __uint_as_float(w << 16); }
; __device__ __forceinline__ float bfhi(unsigned w) { return __uint_as_float(w & 0xffff0000u); }
; __device__ __forceinline__ void attn_item(const bf16_t* __restrict__ Qb, const bf16_t* __restrict__ Kh, const bf16_t* __restrict__ Vh, const bf16_t* __restrict__ Zb, ...
;     ...
;     u32x4 qw[8];
; #pragma unroll
;     for (int d0 = 0; d0 < 8; ++d0) qw[d0] = *reinterpret_cast<const u32x4*>(Qw + d0 * 16);
;     float ss = 0.f;
; #pragma unroll
;     for (int d0 = 0; d0 < 8; ++d0) { const float a0 = bflo(qw[d0].x), a1 = bfhi(qw[d0].x), a2 = bflo(qw[d0].y), a3 = bfhi(qw[d0].y), a4 = bflo(qw[d0].z), a5 = bfhi(qw[d0].z), a6 = bflo(qw[d0].w), a7 = bfhi(qw[d0].w);
;       ss += (a0 * a0 + a1 * a1) + (a2 * a2 + a3 * a3) + (a4 * a4 + a5 * a5) + (a6 * a6 + a7 * a7); }
	v_lshlrev_b32_e32 v93, 16, v57
	v_and_b32_e32 v91, 0xffff0000, v57
	v_and_b32_e32 v155, 0xffff0000, v43
	v_and_b32_e32 v157, 0xffff0000, v42
	v_exp_f32_e32 v79, v0
	v_mov_b32_e32 v94, v93
	v_mov_b32_e32 v95, v91
	v_mul_f32_e32 v0, v91, v91
	v_lshlrev_b32_e32 v113, 16, v49
	v_and_b32_e32 v123, 0xffff0000, v49
	v_lshlrev_b32_e32 v57, 16, v43
	v_lshlrev_b32_e32 v49, 16, v42
	v_mov_b32_e32 v42, v155
	v_mov_b32_e32 v43, v157
	v_pk_fma_f32 v[150:151], v[94:95], v[94:95], v[0:1] op_sel_hi:[1,1,0]
	v_lshlrev_b32_e32 v103, 16, v56
	v_and_b32_e32 v95, 0xffff0000, v56
	v_lshlrev_b32_e32 v125, 16, v48
	v_and_b32_e32 v117, 0xffff0000, v48
	v_lshlrev_b32_e32 v56, 16, v39
	v_and_b32_e32 v154, 0xffff0000, v39
	v_lshlrev_b32_e32 v48, 16, v38
	v_and_b32_e32 v156, 0xffff0000, v38
	v_mov_b32_e32 v38, v57
	v_mov_b32_e32 v39, v49
	v_pk_mul_f32 v[42:43], v[42:43], v[42:43]
	v_and_b32_e32 v159, 0xffff0000, v41
	v_pk_fma_f32 v[38:39], v[38:39], v[38:39], v[42:43]
	v_lshlrev_b32_e32 v43, 16, v41
	v_and_b32_e32 v41, 0xffff0000, v40
	v_and_b32_e32 v118, 0xffff0000, v47
	v_lshlrev_b32_e32 v161, 16, v40
	v_mov_b32_e32 v162, v41
	v_mov_b32_e32 v163, v159
	v_and_b32_e32 v70, 0xffff0000, v63
	v_lshlrev_b32_e32 v72, 16, v62
	v_and_b32_e32 v62, 0xffff0000, v62
	v_lshlrev_b32_e32 v114, 16, v47
	v_and_b32_e32 v120, 0xffff0000, v46
	v_lshlrev_b32_e32 v42, 16, v37
	v_and_b32_e32 v158, 0xffff0000, v37
	v_lshlrev_b32_e32 v160, 16, v36
	v_and_b32_e32 v40, 0xffff0000, v36
	v_mov_b32_e32 v36, v161
	v_mov_b32_e32 v37, v43
	v_pk_mul_f32 v[162:163], v[162:163], v[162:163]
	v_mov_b32_e32 v164, v154
	v_mov_b32_e32 v165, v118
	v_lshlrev_b32_e32 v68, 16, v63
	v_mov_b32_e32 v74, v70
	v_mov_b32_e32 v75, v62
	v_lshlrev_b32_e32 v126, 16, v46
	v_and_b32_e32 v122, 0xffff0000, v45
	v_pk_fma_f32 v[36:37], v[36:37], v[36:37], v[162:163]
	v_mov_b32_e32 v162, v56
	v_mov_b32_e32 v163, v114
	v_pk_mul_f32 v[164:165], v[164:165], v[164:165]
	v_mov_b32_e32 v166, v156
	v_mov_b32_e32 v167, v120
	s_waitcnt vmcnt(4)
	v_lshlrev_b32_e32 v69, 16, v67
	v_and_b32_e32 v71, 0xffff0000, v67
	v_lshlrev_b32_e32 v73, 16, v66
	v_and_b32_e32 v63, 0xffff0000, v66
	v_mov_b32_e32 v66, v68
	v_mov_b32_e32 v67, v72
	v_pk_mul_f32 v[74:75], v[74:75], v[74:75]
	v_lshlrev_b32_e32 v112, 16, v45
	v_and_b32_e32 v116, 0xffff0000, v44
	v_pk_fma_f32 v[162:163], v[162:163], v[162:163], v[164:165]
	v_mov_b32_e32 v164, v48
	v_mov_b32_e32 v165, v126
	v_pk_mul_f32 v[166:167], v[166:167], v[166:167]
	v_mov_b32_e32 v168, v158
	v_mov_b32_e32 v169, v122
	v_pk_fma_f32 v[80:81], v[66:67], v[66:67], v[74:75]
	v_and_b32_e32 v66, 0xffff0000, v61
	v_lshlrev_b32_e32 v76, 16, v60
	v_and_b32_e32 v60, 0xffff0000, v60
	v_lshlrev_b32_e32 v124, 16, v44
	v_pk_fma_f32 v[164:165], v[164:165], v[164:165], v[166:167]
	v_mov_b32_e32 v166, v42
	v_mov_b32_e32 v167, v112
	v_pk_mul_f32 v[168:169], v[168:169], v[168:169]
	v_mov_b32_e32 v170, v40
	v_mov_b32_e32 v171, v116
	v_lshlrev_b32_e32 v74, 16, v61
	v_mov_b32_e32 v84, v60
	v_mov_b32_e32 v85, v66
	v_pk_fma_f32 v[166:167], v[166:167], v[166:167], v[168:169]
	v_mov_b32_e32 v168, v160
	v_mov_b32_e32 v169, v124
	v_pk_mul_f32 v[170:171], v[170:171], v[170:171]
	v_lshlrev_b32_e32 v75, 16, v65
	v_and_b32_e32 v67, 0xffff0000, v65
	v_lshlrev_b32_e32 v77, 16, v64
	v_and_b32_e32 v61, 0xffff0000, v64
	v_mov_b32_e32 v64, v76
	v_mov_b32_e32 v65, v74
	v_pk_mul_f32 v[84:85], v[84:85], v[84:85]
	v_pk_fma_f32 v[168:169], v[168:169], v[168:169], v[170:171]
	v_pk_fma_f32 v[64:65], v[64:65], v[64:65], v[84:85]
	v_lshlrev_b32_e32 v92, 16, v53
	v_and_b32_e32 v90, 0xffff0000, v53
	v_lshlrev_b32_e32 v102, 16, v52
	v_and_b32_e32 v94, 0xffff0000, v52
	v_mov_b32_e32 v52, v103
	v_mov_b32_e32 v53, v95
	v_mul_f32_e32 v0, v95, v95
	v_pk_add_f32 v[166:167], v[168:169], v[166:167]
	v_pk_add_f32 v[64:65], v[64:65], v[64:65] op_sel:[0,1] op_sel_hi:[1,0]
	v_and_b32_e32 v87, 0xffff0000, v58
	v_and_b32_e32 v86, 0xffff0000, v54
	v_pk_fma_f32 v[52:53], v[52:53], v[52:53], v[0:1] op_sel_hi:[1,1,0]
	v_and_b32_e32 v119, 0xffff0000, v51
	v_mov_b32_e32 v46, v113
	v_mov_b32_e32 v47, v123
	v_mul_f32_e32 v0, v123, v123
	v_pk_add_f32 v[36:37], v[36:37], v[36:37] op_sel:[0,1] op_sel_hi:[1,0]
	v_pk_add_f32 v[164:165], v[164:165], v[166:167]
	v_pk_add_f32 v[64:65], v[80:81], v[64:65] op_sel:[1,0] op_sel_hi:[0,1]
	v_lshlrev_b32_e32 v89, 16, v58
	v_lshlrev_b32_e32 v88, 16, v54
	v_lshlrev_b32_e32 v115, 16, v51
	v_and_b32_e32 v121, 0xffff0000, v50
	v_pk_fma_f32 v[46:47], v[46:47], v[46:47], v[0:1] op_sel_hi:[1,1,0]
	v_mov_b32_e32 v44, v125
	v_mov_b32_e32 v45, v117
	v_mul_f32_e32 v0, v117, v117
	v_pk_add_f32 v[36:37], v[38:39], v[36:37] op_sel:[1,0] op_sel_hi:[0,1]
	v_pk_add_f32 v[162:163], v[162:163], v[164:165]
	v_pk_mov_b32 v[164:165], v[118:119], v[86:87] op_sel:[1,0]
	v_pk_add_f32 v[64:65], v[80:81], v[64:65]
	v_lshlrev_b32_e32 v85, 16, v59
	v_lshlrev_b32_e32 v84, 16, v55
	v_and_b32_e32 v81, 0xffff0000, v59
	v_and_b32_e32 v80, 0xffff0000, v55
	v_pk_mul_f32 v[54:55], v[92:93], v[92:93]
	v_pk_mul_f32 v[58:59], v[90:91], v[90:91]
	v_lshlrev_b32_e32 v127, 16, v50
	v_pk_fma_f32 v[44:45], v[44:45], v[44:45], v[0:1] op_sel_hi:[1,1,0]
	v_pk_add_f32 v[36:37], v[38:39], v[36:37]
	v_pk_add_f32 v[38:39], v[162:163], v[162:163] op_sel:[0,1] op_sel_hi:[1,0]
	v_pk_mov_b32 v[162:163], v[114:115], v[88:89] op_sel:[1,0]
	v_pk_mul_f32 v[164:165], v[164:165], v[164:165]
	v_pk_mov_b32 v[166:167], v[120:121], v[94:95] op_sel:[1,0]
	v_pk_fma_f32 v[162:163], v[162:163], v[162:163], v[164:165]
	v_pk_mov_b32 v[164:165], v[126:127], v[102:103] op_sel:[1,0]
	v_pk_mul_f32 v[166:167], v[166:167], v[166:167]
	v_mov_b32_e32 v45, v54
	v_mov_b32_e32 v47, v58
	v_pk_mul_f32 v[146:147], v[84:85], v[84:85]
	v_pk_mul_f32 v[148:149], v[80:81], v[80:81]
	v_pk_fma_f32 v[164:165], v[164:165], v[164:165], v[166:167]
	v_pk_add_f32 v[44:45], v[44:45], v[46:47]
	v_mov_b32_e32 v39, v146
	v_pk_add_f32 v[44:45], v[164:165], v[44:45]
	v_mov_b32_e32 v37, v148
	v_pk_add_f32 v[44:45], v[162:163], v[44:45]
	v_pk_add_f32 v[36:37], v[38:39], v[36:37]
	v_pk_mul_f32 v[132:133], v[74:75], v[74:75]
	v_pk_add_f32 v[36:37], v[36:37], v[44:45]
	v_mov_b32_e32 v44, v81
	v_mov_b32_e32 v45, v63
	v_pk_mul_f32 v[134:135], v[66:67], v[66:67]
	v_mov_b32_e32 v38, v85
	v_mov_b32_e32 v39, v73
	v_pk_mul_f32 v[44:45], v[44:45], v[44:45]
	v_mov_b32_e32 v46, v87
	v_mov_b32_e32 v47, v61
	v_pk_fma_f32 v[38:39], v[38:39], v[38:39], v[44:45]
	v_mov_b32_e32 v44, v89
	v_mov_b32_e32 v45, v77
	v_pk_mul_f32 v[46:47], v[46:47], v[46:47]
	v_mov_b32_e32 v53, v133
	v_mov_b32_e32 v151, v135
	v_pk_mul_f32 v[128:129], v[68:69], v[68:69]
	v_pk_mul_f32 v[130:131], v[70:71], v[70:71]
	v_pk_add_f32 v[36:37], v[36:37], v[36:37] op_sel:[0,1] op_sel_hi:[1,0]
	v_pk_fma_f32 v[44:45], v[44:45], v[44:45], v[46:47]
	v_pk_add_f32 v[46:47], v[52:53], v[150:151]
	v_mov_b32_e32 v37, v129
	v_pk_add_f32 v[44:45], v[44:45], v[46:47]
	v_mov_b32_e32 v65, v131
	v_pk_add_f32 v[38:39], v[38:39], v[44:45]
	v_pk_add_f32 v[36:37], v[36:37], v[64:65]
	s_waitcnt vmcnt(2)
; __device__ __forceinline__ int lane_id_asm() { int r; asm volatile("v_mbcnt_lo_u32_b32 %0, -1, 0\n\tv_mbcnt_hi_u32_b32 %0, -1, %0" : "=v"(r)); return r; }
; __device__ __forceinline__ float bflo(unsigned w) { return __uint_as_float(w << 16); }
; __device__ __forceinline__ void attn_item(const bf16_t* __restrict__ Qb, const bf16_t* __restrict__ Kh, const bf16_t* __restrict__ Vh, const bf16_t* __restrict__ Zb, ...
;     ...
;     { auto rr = __builtin_amdgcn_permlane32_swap(__float_as_uint(ss), __float_as_uint(ss), false, false); ss = __uint_as_float(rr[0]) + __uint_as_float(rr[1]); }
;     const float rstd = __builtin_amdgcn_rsqf(ss * (1.0f / 128.0f) + NORM_EPS) * (SCALE * 1.4426950408889634f);
;     const int hq = lane_id_asm() >> 5;
;     const int spos = qpos0 + wid * QBLK + r32; const float prow = (float)(spos >> 6), pcol = (float)(spos & 63);
; #pragma unroll
;     for (int bb = 0; bb < 4; ++bb) { const int d1 = (bb & 1) + 4 * (bb >> 1), d2 = d1 + 2;
;       const float pos = (bb < 2) ? prow : pcol; const float* g1p = qg + d1 * 16 + hq * 8; const float* g2p = qg + d2 * 16 + hq * 8;
;       const f32x4 g1a = *(const f32x4*)g1p, g1b = *(const f32x4*)(g1p + 4), g2a = *(const f32x4*)g2p, g2b = *(const f32x4*)(g2p + 4);
;       float o1[8], o2[8];
; #pragma unroll
;       for (int e = 0; e < 8; ++e) { const unsigned w1 = (e < 2) ? qw[d1].x : (e < 4) ? qw[d1].y : (e < 6) ? qw[d1].z : qw[d1].w, w2 = (e < 2) ? qw[d2].x : (e < 4) ? qw[d2].y : (e < 6) ? qw[d2].z : qw[d2].w;
;         const float x1 = (e & 1) ? bfhi(w1) : bflo(w1), x2 = (e & 1) ? bfhi(w2) : bflo(w2); const float ga = (e < 4) ? g1a[e & 3] : g1b[e & 3], gb = (e < 4) ? g2a[e & 3] : g2b[e & 3];
;         const int fi = (d1 & 1) * 16 + hq * 8 + e; float rev = pos * (__builtin_amdgcn_exp2f(-(float)fi * (13.287712379549449f / 32.0f)) * 0.15915494309189535f); rev -= floorf(rev);
;         const float sn = sin_rev(rev), cs = cos_rev(rev), y1 = x1 * rstd * ga, y2 = x2 * rstd * gb; o1[e] = y1 * cs - y2 * sn; o2[e] = y2 * cs + y1 * sn; }
; #pragma unroll
;       for (int e = 0; e < 8; ++e) qn2 += o1[e] * o1[e] + o2[e] * o2[e];
;       u32x4 p1 = {cvtpk(o1[0], o1[1]), cvtpk(o1[2], o1[3]), cvtpk(o1[4], o1[5]), cvtpk(o1[6], o1[7])}, p2 = {cvtpk(o2[0], o2[1]), cvtpk(o2[2], o2[3]), cvtpk(o2[4], o2[5]), cvtpk(o2[6], o2[7])};
;       qr[d1] = *reinterpret_cast<bf16x8*>(&p1); qr[d2] = *reinterpret_cast<bf16x8*>(&p2); }
	v_mov_b32_e32 v50, v2
	v_pk_add_f32 v[36:37], v[36:37], v[38:39]
	v_mov_b32_e32 v128, v12
	v_pk_add_f32 v[36:37], v[36:37], v[36:37] op_sel:[0,1] op_sel_hi:[1,0]
	s_waitcnt vmcnt(1)
	v_mov_b32_e32 v129, v34
	v_mov_b32_e32 v0, v36
	s_nop 1
	v_permlane32_swap_b32_e32 v36, v0
	v_add_f32_e32 v0, v36, v0
	v_fmamk_f32 v0, v0, 0x3c000000, v217
	v_rsq_f32_e32 v0, v0
	v_mov_b32_e32 v36, v10
	v_mov_b32_e32 v37, v32
	v_mov_b32_e32 v32, v11
	v_mul_f32_e32 v0, 0x3e0293ee, v0
	v_pk_mul_f32 v[38:39], v[0:1], v[160:161] op_sel_hi:[0,1]
	v_pk_mul_f32 v[38:39], v[36:37], v[38:39]
	v_mov_b32_e32 v36, v105
	v_mov_b32_e32 v37, v104
	v_mul_f32_e32 v2, v39, v104
	v_pk_mul_f32 v[40:41], v[0:1], v[40:41] op_sel_hi:[0,1]
	v_pk_fma_f32 v[36:37], v[38:39], v[36:37], v[2:3] op_sel_hi:[1,1,0] neg_lo:[0,0,1] neg_hi:[0,0,1]
	v_mul_f32_e32 v2, v39, v105
	v_pk_mul_f32 v[10:11], v[32:33], v[40:41]
	v_pk_fma_f32 v[38:39], v[38:39], v[104:105], v[2:3] op_sel_hi:[1,1,0]
	v_mul_f32_e32 v2, v11, v83
	v_pk_fma_f32 v[32:33], v[10:11], v[82:83], v[2:3] op_sel_hi:[1,1,0] neg_lo:[0,0,1] neg_hi:[0,0,1]
	v_mov_b32_e32 v40, v83
	v_mov_b32_e32 v41, v82
	v_mul_f32_e32 v2, v11, v82
	v_pk_fma_f32 v[40:41], v[10:11], v[40:41], v[2:3] op_sel_hi:[1,1,0]
	v_pk_mul_f32 v[10:11], v[0:1], v[42:43] op_sel_hi:[0,1]
	v_pk_mul_f32 v[10:11], v[128:129], v[10:11]
	v_mov_b32_e32 v42, v107
	v_mov_b32_e32 v43, v106
	v_mul_f32_e32 v2, v11, v106
	v_pk_fma_f32 v[42:43], v[10:11], v[42:43], v[2:3] op_sel_hi:[1,1,0] neg_lo:[0,0,1] neg_hi:[0,0,1]
	v_mul_f32_e32 v2, v11, v107
	v_pk_fma_f32 v[44:45], v[10:11], v[106:107], v[2:3] op_sel_hi:[1,1,0]
	v_pk_mul_f32 v[10:11], v[0:1], v[158:159] op_sel_hi:[0,1]
	v_mov_b32_e32 v34, v13
	v_pk_mul_f32 v[10:11], v[34:35], v[10:11]
	v_mov_b32_e32 v12, v97
	v_mul_f32_e32 v2, v11, v97
	v_pk_fma_f32 v[34:35], v[10:11], v[96:97], v[2:3] op_sel_hi:[1,1,0] neg_lo:[0,0,1] neg_hi:[0,0,1]
	v_mov_b32_e32 v13, v96
	v_mul_f32_e32 v2, v11, v96
	s_waitcnt vmcnt(0)
	v_mov_b32_e32 v51, v6
	v_pk_fma_f32 v[46:47], v[10:11], v[12:13], v[2:3] op_sel_hi:[1,1,0]
	v_pk_mul_f32 v[10:11], v[0:1], v[48:49] op_sel_hi:[0,1]
	v_pk_mul_f32 v[10:11], v[50:51], v[10:11]
	v_mov_b32_e32 v12, v109
	v_mov_b32_e32 v13, v108
	v_mul_f32_e32 v2, v11, v108
	v_pk_fma_f32 v[48:49], v[10:11], v[12:13], v[2:3] op_sel_hi:[1,1,0] neg_lo:[0,0,1] neg_hi:[0,0,1]
	v_mul_f32_e32 v2, v11, v109
	v_pk_fma_f32 v[50:51], v[10:11], v[108:109], v[2:3] op_sel_hi:[1,1,0]
	v_pk_mul_f32 v[10:11], v[0:1], v[156:157] op_sel_hi:[0,1]
	v_mov_b32_e32 v6, v3
	v_pk_mul_f32 v[2:3], v[6:7], v[10:11]
	v_mov_b32_e32 v152, v4
	v_mul_f32_e32 v4, v3, v101
	v_pk_fma_f32 v[52:53], v[2:3], v[100:101], v[4:5] op_sel_hi:[1,1,0] neg_lo:[0,0,1] neg_hi:[0,0,1]
	v_mov_b32_e32 v6, v101
	v_mov_b32_e32 v7, v100
	v_mul_f32_e32 v4, v3, v100
	v_mov_b32_e32 v153, v8
	v_pk_fma_f32 v[54:55], v[2:3], v[6:7], v[4:5] op_sel_hi:[1,1,0]
	v_pk_mul_f32 v[2:3], v[0:1], v[56:57] op_sel_hi:[0,1]
	v_pk_mul_f32 v[2:3], v[152:153], v[2:3]
	v_mov_b32_e32 v6, v111
	v_mov_b32_e32 v7, v110
	v_mul_f32_e32 v4, v3, v110
	v_pk_fma_f32 v[56:57], v[2:3], v[6:7], v[4:5] op_sel_hi:[1,1,0] neg_lo:[0,0,1] neg_hi:[0,0,1]
	v_mul_f32_e32 v4, v3, v111
	v_pk_fma_f32 v[58:59], v[2:3], v[110:111], v[4:5] op_sel_hi:[1,1,0]
	v_pk_mul_f32 v[2:3], v[0:1], v[154:155] op_sel_hi:[0,1]
	v_mov_b32_e32 v8, v5
	v_pk_mul_f32 v[2:3], v[8:9], v[2:3]
	v_cvt_pk_bf16_f32 v152, v36, v32
	v_cvt_pk_bf16_f32 v153, v42, v34
	v_cvt_pk_bf16_f32 v154, v48, v52
	v_add_u32_e32 v96, 17, v78
	v_mul_f32_e32 v4, v3, v99
	v_pk_fma_f32 v[64:65], v[2:3], v[98:99], v[4:5] op_sel_hi:[1,1,0] neg_lo:[0,0,1] neg_hi:[0,0,1]
	v_mov_b32_e32 v4, v99
	v_mov_b32_e32 v5, v98
	v_mul_f32_e32 v6, v3, v98
	v_pk_fma_f32 v[82:83], v[2:3], v[4:5], v[6:7] op_sel_hi:[1,1,0]
	v_cvt_pk_bf16_f32 v155, v56, v64
	v_cvt_pk_bf16_f32 v148, v38, v40
	v_cvt_pk_bf16_f32 v149, v44, v46
	v_cvt_pk_bf16_f32 v150, v50, v54
	v_cvt_f32_i32_e32 v96, v96
	v_cvt_pk_bf16_f32 v151, v58, v82
	global_load_dwordx4 v[2:5], v[14:15], off offset:80
	global_load_dwordx4 v[6:9], v[14:15], off offset:64
	global_load_dwordx4 v[10:13], v[14:15], off offset:192
	global_load_dwordx4 v[128:131], v[14:15], off offset:208
	v_mul_f32_e32 v176, 0.15915494, v79
	v_mul_f32_e32 v96, 0xbed49a78, v96
	v_exp_f32_e32 v98, v96
	v_mul_f32_e32 v79, v176, v145
	v_floor_f32_e32 v79, v79
	v_fma_f32 v79, v176, v145, -v79
	v_mul_f32_e32 v177, 0.15915494, v98
	v_add_u32_e32 v98, 18, v78
	v_cvt_f32_i32_e32 v98, v98
	v_sin_f32_e32 v96, v79
	v_cos_f32_e32 v97, v79
	v_mul_f32_e32 v79, v177, v145
	v_floor_f32_e32 v79, v79
	v_fma_f32 v79, v177, v145, -v79
	v_mul_f32_e32 v98, 0xbed49a78, v98
	v_sin_f32_e32 v99, v79
	v_exp_f32_e32 v100, v98
	v_cos_f32_e32 v98, v79
	v_add_u32_e32 v79, 19, v78
	v_cvt_f32_i32_e32 v79, v79
	v_add_u32_e32 v104, 20, v78
	v_cvt_f32_i32_e32 v104, v104
	v_mul_f32_e32 v178, 0.15915494, v100
	v_mul_f32_e32 v79, 0xbed49a78, v79
	v_exp_f32_e32 v79, v79
	v_mul_f32_e32 v104, 0xbed49a78, v104
	v_exp_f32_e32 v104, v104
	v_mul_f32_e32 v100, v178, v145
	v_mul_f32_e32 v179, 0.15915494, v79
	v_mul_f32_e32 v79, v179, v145
	v_floor_f32_e32 v79, v79
	v_fma_f32 v79, v179, v145, -v79
	v_mul_f32_e32 v180, 0.15915494, v104
	v_sin_f32_e32 v107, v79
	v_cos_f32_e32 v106, v79
	v_add_u32_e32 v79, 21, v78
	v_mul_f32_e32 v104, v180, v145
	v_cvt_f32_i32_e32 v79, v79
	v_floor_f32_e32 v104, v104
	v_fma_f32 v104, v180, v145, -v104
	v_sin_f32_e32 v110, v104
	v_cos_f32_e32 v111, v104
	v_add_u32_e32 v104, 22, v78
	v_add_u32_e32 v78, 23, v78
	v_cvt_f32_i32_e32 v104, v104
	v_cvt_f32_i32_e32 v78, v78
	v_mul_f32_e32 v79, 0xbed49a78, v79
	v_exp_f32_e32 v79, v79
	v_mul_f32_e32 v104, 0xbed49a78, v104
	v_mul_f32_e32 v78, 0xbed49a78, v78
	v_exp_f32_e32 v104, v104
	v_exp_f32_e32 v78, v78
	v_mul_f32_e32 v181, 0.15915494, v79
	v_mul_f32_e32 v79, v181, v145
	v_floor_f32_e32 v79, v79
	v_fma_f32 v79, v181, v145, -v79
	v_mul_f32_e32 v182, 0.15915494, v104
	v_mul_f32_e32 v183, 0.15915494, v78
	v_sin_f32_e32 v133, v79
	v_cos_f32_e32 v132, v79
	v_mul_f32_e32 v79, v182, v145
	v_mul_f32_e32 v78, v183, v145
	v_floor_f32_e32 v79, v79
	v_floor_f32_e32 v78, v78
	v_fma_f32 v79, v182, v145, -v79
	v_fma_f32 v78, v183, v145, -v78
	v_sin_f32_e32 v134, v79
	v_cos_f32_e32 v135, v79
	v_sin_f32_e32 v147, v78
	v_cos_f32_e32 v146, v78
	v_pk_mul_f32 v[78:79], v[0:1], v[124:125] op_sel_hi:[0,1]
	v_floor_f32_e32 v100, v100
	v_fma_f32 v101, v178, v145, -v100
	v_sin_f32_e32 v100, v101
	v_cos_f32_e32 v101, v101
	v_pk_mul_f32 v[102:103], v[0:1], v[102:103] op_sel_hi:[0,1]
	v_pk_mul_f32 v[94:95], v[0:1], v[94:95] op_sel_hi:[0,1]
	s_waitcnt vmcnt(2)
; __device__ __forceinline__ unsigned cvtpk(float lo, float hi) { unsigned r; asm volatile("v_cvt_pk_bf16_f32 %0, %1, %2" : "=v"(r) : "v"(lo), "v"(hi)); return r; }
; __device__ __forceinline__ float bflo(unsigned w) { return __uint_as_float(w << 16); }
; __device__ __forceinline__ float bfhi(unsigned w) { return __uint_as_float(w & 0xffff0000u); }
; __device__ __forceinline__ void attn_item(const bf16_t* __restrict__ Qb, const bf16_t* __restrict__ Kh, const bf16_t* __restrict__ Vh, const bf16_t* __restrict__ Zb, ...
;     ...
;     const int spos = qpos0 + wid * QBLK + r32; const float prow = (float)(spos >> 6), pcol = (float)(spos & 63);
; #pragma unroll
;     for (int bb = 0; bb < 4; ++bb) { const int d1 = (bb & 1) + 4 * (bb >> 1), d2 = d1 + 2;
;       const float pos = (bb < 2) ? prow : pcol; const float* g1p = qg + d1 * 16 + hq * 8; const float* g2p = qg + d2 * 16 + hq * 8;
;       const f32x4 g1a = *(const f32x4*)g1p, g1b = *(const f32x4*)(g1p + 4), g2a = *(const f32x4*)g2p, g2b = *(const f32x4*)(g2p + 4);
;       float o1[8], o2[8];
; #pragma unroll
;       for (int e = 0; e < 8; ++e) { const unsigned w1 = (e < 2) ? qw[d1].x : (e < 4) ? qw[d1].y : (e < 6) ? qw[d1].z : qw[d1].w, w2 = (e < 2) ? qw[d2].x : (e < 4) ? qw[d2].y : (e < 6) ? qw[d2].z : qw[d2].w;
;         const float x1 = (e & 1) ? bfhi(w1) : bflo(w1), x2 = (e & 1) ? bfhi(w2) : bflo(w2); const float ga = (e < 4) ? g1a[e & 3] : g1b[e & 3], gb = (e < 4) ? g2a[e & 3] : g2b[e & 3];
;         const int fi = (d1 & 1) * 16 + hq * 8 + e; float rev = pos * (__builtin_amdgcn_exp2f(-(float)fi * (13.287712379549449f / 32.0f)) * 0.15915494309189535f); rev -= floorf(rev);
;         const float sn = sin_rev(rev), cs = cos_rev(rev), y1 = x1 * rstd * ga, y2 = x2 * rstd * gb; o1[e] = y1 * cs - y2 * sn; o2[e] = y2 * cs + y1 * sn; }
; #pragma unroll
;       for (int e = 0; e < 8; ++e) qn2 += o1[e] * o1[e] + o2[e] * o2[e];
;       u32x4 p1 = {cvtpk(o1[0], o1[1]), cvtpk(o1[2], o1[3]), cvtpk(o1[4], o1[5]), cvtpk(o1[6], o1[7])}, p2 = {cvtpk(o2[0], o2[1]), cvtpk(o2[2], o2[3]), cvtpk(o2[4], o2[5]), cvtpk(o2[6], o2[7])};
;       qr[d1] = *reinterpret_cast<bf16x8*>(&p1); qr[d2] = *reinterpret_cast<bf16x8*>(&p2); }
;   }
;   const int sr = tid >> 4, sc = (tid & 15) * 8, vst0 = v_st_nat(sr, sc), vst1 = v_st_nat(32 + sr, sc), kst0 = KOFF + KSWZ(sr, sc * 2), kst1 = KOFF + KSWZ(32 + sr, sc * 2);
	v_mov_b32_e32 v104, v6
	s_waitcnt vmcnt(1)
	v_mov_b32_e32 v105, v10
	v_pk_mul_f32 v[104:105], v[78:79], v[104:105]
	v_mov_b32_e32 v78, v97
	v_mov_b32_e32 v79, v96
	v_mul_f32_e32 v6, v96, v105
	v_pk_fma_f32 v[78:79], v[78:79], v[104:105], v[6:7] op_sel_hi:[1,1,0] neg_lo:[0,0,1] neg_hi:[0,0,1]
	v_mul_f32_e32 v6, v97, v105
	v_pk_fma_f32 v[96:97], v[96:97], v[104:105], v[6:7] op_sel_hi:[1,1,0]
	v_pk_mul_f32 v[104:105], v[0:1], v[116:117] op_sel_hi:[0,1]
	v_mov_b32_e32 v10, v7
	v_pk_mul_f32 v[6:7], v[104:105], v[10:11]
	v_pk_mul_f32 v[76:77], v[0:1], v[76:77] op_sel_hi:[0,1]
	v_mul_f32_e32 v10, v99, v7
	v_pk_fma_f32 v[104:105], v[98:99], v[6:7], v[10:11] op_sel_hi:[1,1,0] neg_lo:[0,0,1] neg_hi:[0,0,1]
	v_mov_b32_e32 v10, v99
	v_mov_b32_e32 v11, v98
	v_mul_f32_e32 v98, v98, v7
	v_pk_fma_f32 v[108:109], v[10:11], v[6:7], v[98:99] op_sel_hi:[1,1,0]
	v_pk_mul_f32 v[6:7], v[0:1], v[112:113] op_sel_hi:[0,1]
	v_mov_b32_e32 v10, v8
	v_mov_b32_e32 v11, v12
	v_pk_mul_f32 v[6:7], v[6:7], v[10:11]
	v_mov_b32_e32 v10, v101
	v_mov_b32_e32 v11, v100
	v_mul_f32_e32 v8, v100, v7
	v_pk_fma_f32 v[112:113], v[10:11], v[6:7], v[8:9] op_sel_hi:[1,1,0] neg_lo:[0,0,1] neg_hi:[0,0,1]
	v_mul_f32_e32 v8, v101, v7
	v_pk_fma_f32 v[116:117], v[100:101], v[6:7], v[8:9] op_sel_hi:[1,1,0]
	v_pk_mul_f32 v[6:7], v[0:1], v[122:123] op_sel_hi:[0,1]
	v_mov_b32_e32 v12, v9
	v_pk_mul_f32 v[6:7], v[6:7], v[12:13]
	v_cvt_pk_bf16_f32 v160, v78, v104
	s_mulk_i32 s0, 0x2080
	v_mul_f32_e32 v8, v107, v7
	v_pk_fma_f32 v[122:123], v[106:107], v[6:7], v[8:9] op_sel_hi:[1,1,0] neg_lo:[0,0,1] neg_hi:[0,0,1]
	v_mov_b32_e32 v8, v107
	v_mov_b32_e32 v9, v106
	v_mul_f32_e32 v10, v106, v7
	v_pk_fma_f32 v[124:125], v[8:9], v[6:7], v[10:11] op_sel_hi:[1,1,0]
	v_pk_mul_f32 v[6:7], v[0:1], v[126:127] op_sel_hi:[0,1]
	v_mov_b32_e32 v8, v2
	s_waitcnt vmcnt(0)
	v_mov_b32_e32 v9, v128
	v_pk_mul_f32 v[6:7], v[6:7], v[8:9]
	v_mov_b32_e32 v8, v111
	v_mov_b32_e32 v9, v110
	v_mul_f32_e32 v2, v110, v7
	v_pk_fma_f32 v[98:99], v[8:9], v[6:7], v[2:3] op_sel_hi:[1,1,0] neg_lo:[0,0,1] neg_hi:[0,0,1]
	v_mul_f32_e32 v2, v111, v7
	v_pk_fma_f32 v[100:101], v[110:111], v[6:7], v[2:3] op_sel_hi:[1,1,0]
	v_pk_mul_f32 v[6:7], v[0:1], v[120:121] op_sel_hi:[0,1]
	v_mov_b32_e32 v128, v3
	v_pk_mul_f32 v[2:3], v[6:7], v[128:129]
	v_cvt_pk_bf16_f32 v161, v112, v122
	v_and_b32_e32 v128, 63, v136
	v_mul_f32_e32 v6, v133, v3
	v_pk_fma_f32 v[106:107], v[132:133], v[2:3], v[6:7] op_sel_hi:[1,1,0] neg_lo:[0,0,1] neg_hi:[0,0,1]
	v_mov_b32_e32 v6, v133
	v_mov_b32_e32 v7, v132
	v_mul_f32_e32 v8, v132, v3
	v_pk_fma_f32 v[110:111], v[6:7], v[2:3], v[8:9] op_sel_hi:[1,1,0]
	v_pk_mul_f32 v[2:3], v[0:1], v[114:115] op_sel_hi:[0,1]
	v_mov_b32_e32 v6, v4
	v_mov_b32_e32 v7, v130
	v_pk_mul_f32 v[2:3], v[2:3], v[6:7]
	v_mov_b32_e32 v6, v135
	v_mov_b32_e32 v7, v134
	v_mul_f32_e32 v4, v134, v3
	v_pk_fma_f32 v[114:115], v[6:7], v[2:3], v[4:5] op_sel_hi:[1,1,0] neg_lo:[0,0,1] neg_hi:[0,0,1]
	v_mul_f32_e32 v4, v135, v3
	v_pk_fma_f32 v[120:121], v[134:135], v[2:3], v[4:5] op_sel_hi:[1,1,0]
	v_pk_mul_f32 v[2:3], v[0:1], v[118:119] op_sel_hi:[0,1]
	v_mov_b32_e32 v130, v5
	v_pk_mul_f32 v[2:3], v[2:3], v[130:131]
	v_cvt_pk_bf16_f32 v162, v98, v106
	v_cvt_f32_ubyte0_e32 v189, v128
	v_mul_f32_e32 v4, v147, v3
	v_pk_fma_f32 v[118:119], v[146:147], v[2:3], v[4:5] op_sel_hi:[1,1,0] neg_lo:[0,0,1] neg_hi:[0,0,1]
	v_mov_b32_e32 v4, v147
	v_mov_b32_e32 v5, v146
	v_mul_f32_e32 v6, v146, v3
	v_pk_fma_f32 v[126:127], v[4:5], v[2:3], v[6:7] op_sel_hi:[1,1,0]
	v_cvt_pk_bf16_f32 v163, v114, v118
	v_cvt_pk_bf16_f32 v156, v96, v108
	v_cvt_pk_bf16_f32 v157, v116, v124
	v_cvt_pk_bf16_f32 v158, v100, v110
	v_mul_f32_e32 v130, v138, v189
	v_cvt_pk_bf16_f32 v159, v120, v126
	global_load_dwordx4 v[2:5], v[14:15], off offset:256
	global_load_dwordx4 v[6:9], v[14:15], off offset:384
	global_load_dwordx4 v[10:13], v[14:15], off offset:272
	global_load_dwordx4 v[164:167], v[14:15], off offset:400
	v_mul_f32_e32 v128, v137, v189
	v_floor_f32_e32 v130, v130
	v_floor_f32_e32 v128, v128
	v_fma_f32 v130, v138, v189, -v130
	v_mul_f32_e32 v138, v142, v189
	v_fma_f32 v129, v137, v189, -v128
	v_floor_f32_e32 v138, v138
	v_sin_f32_e32 v128, v129
	v_cos_f32_e32 v129, v129
	v_fma_f32 v138, v142, v189, -v138
	v_mul_f32_e32 v142, v144, v189
	v_floor_f32_e32 v142, v142
	v_fma_f32 v142, v144, v189, -v142
	v_sin_f32_e32 v131, v130
	v_cos_f32_e32 v130, v130
	v_mul_f32_e32 v132, v139, v189
	v_floor_f32_e32 v132, v132
	v_fma_f32 v133, v139, v189, -v132
	v_sin_f32_e32 v132, v133
	v_cos_f32_e32 v133, v133
	v_mul_f32_e32 v134, v140, v189
	v_floor_f32_e32 v134, v134
	v_fma_f32 v134, v140, v189, -v134
	v_sin_f32_e32 v135, v134
	v_cos_f32_e32 v134, v134
	v_mul_f32_e32 v136, v141, v189
	v_floor_f32_e32 v136, v136
	v_fma_f32 v137, v141, v189, -v136
	v_sin_f32_e32 v136, v137
	v_cos_f32_e32 v137, v137
	v_sin_f32_e32 v139, v138
	v_cos_f32_e32 v138, v138
	v_mul_f32_e32 v140, v143, v189
	v_floor_f32_e32 v140, v140
	v_fma_f32 v141, v143, v189, -v140
	v_sin_f32_e32 v140, v141
	v_cos_f32_e32 v141, v141
	v_sin_f32_e32 v143, v142
	v_cos_f32_e32 v142, v142
	s_add_u32 s0, s42, s0
	s_addc_u32 s1, s43, 0
	v_lshlrev_b32_e32 v206, 3, v186
	s_add_u32 s0, s0, s8
	s_addc_u32 s1, s1, 0
	v_pk_mul_f32 v[38:39], v[38:39], v[38:39]
	v_lshlrev_b32_e32 v221, 8, v187
	v_pk_fma_f32 v[36:37], v[36:37], v[36:37], v[38:39]
	v_pk_mul_f32 v[38:39], v[40:41], v[40:41]
	v_and_b32_e32 v208, 63, v186
	v_pk_fma_f32 v[32:33], v[32:33], v[32:33], v[38:39]
	v_and_b32_e32 v39, 24, v206
	v_pk_add_f32 v[32:33], v[36:37], v[32:33]
	v_pk_mul_f32 v[36:37], v[44:45], v[44:45]
	s_cmp_lg_u32 0, -1
	v_pk_fma_f32 v[36:37], v[42:43], v[42:43], v[36:37]
	s_mul_i32 s9, s6, 0x8200000
	v_pk_add_f32 v[32:33], v[36:37], v[32:33]
	v_pk_mul_f32 v[36:37], v[46:47], v[46:47]
	s_cselect_b32 s6, 0, 0
	v_pk_fma_f32 v[34:35], v[34:35], v[34:35], v[36:37]
	v_lshrrev_b32_e32 v36, 5, v186
	v_pk_add_f32 v[32:33], v[34:35], v[32:33]
	v_pk_mul_f32 v[34:35], v[50:51], v[50:51]
	v_bfe_u32 v37, v206, 5, 2
	v_pk_fma_f32 v[34:35], v[48:49], v[48:49], v[34:35]
	v_and_or_b32 v36, v36, s58, v37
	v_pk_add_f32 v[32:33], v[34:35], v[32:33]
	v_pk_mul_f32 v[34:35], v[54:55], v[54:55]
	v_mov_b32_e32 v244, 1.0
	v_pk_fma_f32 v[34:35], v[52:53], v[52:53], v[34:35]
	s_mov_b32 s76, 0x10000
	v_pk_add_f32 v[32:33], v[34:35], v[32:33]
	v_pk_mul_f32 v[34:35], v[58:59], v[58:59]
	v_pk_mul_f32 v[58:59], v[120:121], v[120:121]
	v_pk_fma_f32 v[34:35], v[56:57], v[56:57], v[34:35]
	s_mov_b32 s77, 0x8000
	s_waitcnt vmcnt(3)
; __device__ __forceinline__ unsigned cvtpk(float lo, float hi) { unsigned r; asm volatile("v_cvt_pk_bf16_f32 %0, %1, %2" : "=v"(r) : "v"(lo), "v"(hi)); return r; }
; __device__ __forceinline__ float bflo(unsigned w) { return __uint_as_float(w << 16); }
; __device__ __forceinline__ float bfhi(unsigned w) { return __uint_as_float(w & 0xffff0000u); }
; __device__ __forceinline__ void attn_item(const bf16_t* __restrict__ Qb, const bf16_t* __restrict__ Kh, const bf16_t* __restrict__ Vh, const bf16_t* __restrict__ Zb, ...
;     ...
;     const int spos = qpos0 + wid * QBLK + r32; const float prow = (float)(spos >> 6), pcol = (float)(spos & 63);
; #pragma unroll
;     for (int bb = 0; bb < 4; ++bb) { const int d1 = (bb & 1) + 4 * (bb >> 1), d2 = d1 + 2;
;       const float pos = (bb < 2) ? prow : pcol; const float* g1p = qg + d1 * 16 + hq * 8; const float* g2p = qg + d2 * 16 + hq * 8;
;       const f32x4 g1a = *(const f32x4*)g1p, g1b = *(const f32x4*)(g1p + 4), g2a = *(const f32x4*)g2p, g2b = *(const f32x4*)(g2p + 4);
;       float o1[8], o2[8];
; #pragma unroll
;       for (int e = 0; e < 8; ++e) { const unsigned w1 = (e < 2) ? qw[d1].x : (e < 4) ? qw[d1].y : (e < 6) ? qw[d1].z : qw[d1].w, w2 = (e < 2) ? qw[d2].x : (e < 4) ? qw[d2].y : (e < 6) ? qw[d2].z : qw[d2].w;
;         const float x1 = (e & 1) ? bfhi(w1) : bflo(w1), x2 = (e & 1) ? bfhi(w2) : bflo(w2); const float ga = (e < 4) ? g1a[e & 3] : g1b[e & 3], gb = (e < 4) ? g2a[e & 3] : g2b[e & 3];
;         const int fi = (d1 & 1) * 16 + hq * 8 + e; float rev = pos * (__builtin_amdgcn_exp2f(-(float)fi * (13.287712379549449f / 32.0f)) * 0.15915494309189535f); rev -= floorf(rev);
;         const float sn = sin_rev(rev), cs = cos_rev(rev), y1 = x1 * rstd * ga, y2 = x2 * rstd * gb; o1[e] = y1 * cs - y2 * sn; o2[e] = y2 * cs + y1 * sn; }
; #pragma unroll
;       for (int e = 0; e < 8; ++e) qn2 += o1[e] * o1[e] + o2[e] * o2[e];
;       u32x4 p1 = {cvtpk(o1[0], o1[1]), cvtpk(o1[2], o1[3]), cvtpk(o1[4], o1[5]), cvtpk(o1[6], o1[7])}, p2 = {cvtpk(o2[0], o2[1]), cvtpk(o2[2], o2[3]), cvtpk(o2[4], o2[5]), cvtpk(o2[6], o2[7])};
;       qr[d1] = *reinterpret_cast<bf16x8*>(&p1); qr[d2] = *reinterpret_cast<bf16x8*>(&p2); }
;   }
;   const int sr = tid >> 4, sc = (tid & 15) * 8, vst0 = v_st_nat(sr, sc), vst1 = v_st_nat(32 + sr, sc), kst0 = KOFF + KSWZ(sr, sc * 2), kst1 = KOFF + KSWZ(32 + sr, sc * 2);
	v_mov_b32_e32 v144, v2
	s_waitcnt vmcnt(2)
	v_mov_b32_e32 v145, v6
	v_pk_mul_f32 v[144:145], v[102:103], v[144:145]
	v_mov_b32_e32 v102, v129
	v_mov_b32_e32 v103, v128
	v_mul_f32_e32 v2, v128, v145
	v_pk_fma_f32 v[102:103], v[102:103], v[144:145], v[2:3] op_sel_hi:[1,1,0] neg_lo:[0,0,1] neg_hi:[0,0,1]
	v_mul_f32_e32 v2, v129, v145
	v_mov_b32_e32 v6, v3
	v_pk_fma_f32 v[128:129], v[128:129], v[144:145], v[2:3] op_sel_hi:[1,1,0]
	v_pk_mul_f32 v[2:3], v[94:95], v[6:7]
	v_mul_f32_e32 v144, v177, v189
	v_mul_f32_e32 v6, v131, v3
	v_pk_fma_f32 v[94:95], v[130:131], v[2:3], v[6:7] op_sel_hi:[1,1,0] neg_lo:[0,0,1] neg_hi:[0,0,1]
	v_mov_b32_e32 v6, v131
	v_mov_b32_e32 v7, v130
	v_mul_f32_e32 v130, v130, v3
	v_pk_fma_f32 v[130:131], v[6:7], v[2:3], v[130:131] op_sel_hi:[1,1,0]
	v_pk_mul_f32 v[2:3], v[0:1], v[92:93] op_sel_hi:[0,1]
	v_mov_b32_e32 v6, v4
	v_mov_b32_e32 v7, v8
	v_pk_mul_f32 v[2:3], v[2:3], v[6:7]
	v_mov_b32_e32 v6, v133
	v_mov_b32_e32 v7, v132
	v_mul_f32_e32 v4, v132, v3
	v_pk_fma_f32 v[92:93], v[6:7], v[2:3], v[4:5] op_sel_hi:[1,1,0] neg_lo:[0,0,1] neg_hi:[0,0,1]
	v_mul_f32_e32 v4, v133, v3
	v_pk_fma_f32 v[132:133], v[132:133], v[2:3], v[4:5] op_sel_hi:[1,1,0]
	v_pk_mul_f32 v[2:3], v[0:1], v[90:91] op_sel_hi:[0,1]
	v_mov_b32_e32 v8, v5
	v_pk_mul_f32 v[2:3], v[2:3], v[8:9]
	v_cvt_pk_bf16_f32 v168, v102, v94
	v_floor_f32_e32 v144, v144
	v_mul_f32_e32 v4, v135, v3
	v_pk_fma_f32 v[90:91], v[134:135], v[2:3], v[4:5] op_sel_hi:[1,1,0] neg_lo:[0,0,1] neg_hi:[0,0,1]
	v_mov_b32_e32 v4, v135
	v_mov_b32_e32 v5, v134
	v_mul_f32_e32 v6, v134, v3
	v_pk_fma_f32 v[134:135], v[4:5], v[2:3], v[6:7] op_sel_hi:[1,1,0]
	v_pk_mul_f32 v[2:3], v[0:1], v[88:89] op_sel_hi:[0,1]
	s_waitcnt vmcnt(1)
	v_mov_b32_e32 v4, v10
	s_waitcnt vmcnt(0)
	v_mov_b32_e32 v5, v164
	v_pk_mul_f32 v[2:3], v[2:3], v[4:5]
	v_mov_b32_e32 v4, v137
	v_mov_b32_e32 v5, v136
	v_mul_f32_e32 v6, v136, v3
	v_pk_fma_f32 v[88:89], v[4:5], v[2:3], v[6:7] op_sel_hi:[1,1,0] neg_lo:[0,0,1] neg_hi:[0,0,1]
	v_mul_f32_e32 v4, v137, v3
	v_pk_fma_f32 v[136:137], v[136:137], v[2:3], v[4:5] op_sel_hi:[1,1,0]
	v_pk_mul_f32 v[2:3], v[0:1], v[86:87] op_sel_hi:[0,1]
	v_mov_b32_e32 v164, v11
	v_pk_mul_f32 v[2:3], v[2:3], v[164:165]
	v_cvt_pk_bf16_f32 v169, v92, v90
	v_fma_f32 v144, v177, v189, -v144
	v_mul_f32_e32 v4, v139, v3
	v_pk_fma_f32 v[86:87], v[138:139], v[2:3], v[4:5] op_sel_hi:[1,1,0] neg_lo:[0,0,1] neg_hi:[0,0,1]
	v_mov_b32_e32 v4, v139
	v_mov_b32_e32 v5, v138
	v_mul_f32_e32 v6, v138, v3
	v_pk_fma_f32 v[138:139], v[4:5], v[2:3], v[6:7] op_sel_hi:[1,1,0]
	v_pk_mul_f32 v[2:3], v[0:1], v[84:85] op_sel_hi:[0,1]
	v_mov_b32_e32 v4, v12
	v_mov_b32_e32 v5, v166
	v_pk_mul_f32 v[2:3], v[2:3], v[4:5]
	v_mov_b32_e32 v4, v141
	v_mov_b32_e32 v5, v140
	v_mul_f32_e32 v6, v140, v3
	v_pk_fma_f32 v[84:85], v[4:5], v[2:3], v[6:7] op_sel_hi:[1,1,0] neg_lo:[0,0,1] neg_hi:[0,0,1]
	v_mul_f32_e32 v4, v141, v3
	v_pk_fma_f32 v[140:141], v[140:141], v[2:3], v[4:5] op_sel_hi:[1,1,0]
	v_pk_mul_f32 v[2:3], v[0:1], v[80:81] op_sel_hi:[0,1]
	v_mov_b32_e32 v166, v13
	v_pk_mul_f32 v[2:3], v[2:3], v[166:167]
	v_cvt_pk_bf16_f32 v170, v88, v86
	v_sin_f32_e32 v147, v144
	v_mul_f32_e32 v4, v143, v3
	v_pk_fma_f32 v[80:81], v[142:143], v[2:3], v[4:5] op_sel_hi:[1,1,0] neg_lo:[0,0,1] neg_hi:[0,0,1]
	v_mov_b32_e32 v4, v143
	v_mov_b32_e32 v5, v142
	v_mul_f32_e32 v6, v142, v3
	v_pk_fma_f32 v[142:143], v[4:5], v[2:3], v[6:7] op_sel_hi:[1,1,0]
	v_cvt_pk_bf16_f32 v171, v84, v80
	v_cvt_pk_bf16_f32 v164, v128, v130
	v_cvt_pk_bf16_f32 v165, v132, v134
	v_cvt_pk_bf16_f32 v166, v136, v138
	v_cos_f32_e32 v146, v144
	v_cvt_pk_bf16_f32 v167, v140, v142
	global_load_dwordx4 v[2:5], v[14:15], off offset:320
	global_load_dwordx4 v[6:9], v[14:15], off offset:448
	global_load_dwordx4 v[10:13], v[14:15], off offset:336
	global_load_dwordx4 v[172:175], v[14:15], off offset:464
	v_mul_f32_e32 v144, v178, v189
	v_mul_f32_e32 v14, v176, v189
	v_floor_f32_e32 v144, v144
	v_floor_f32_e32 v14, v14
	v_fma_f32 v144, v178, v189, -v144
	v_fma_f32 v15, v176, v189, -v14
	v_sin_f32_e32 v176, v144
	v_cos_f32_e32 v177, v144
	v_mul_f32_e32 v144, v179, v189
	v_floor_f32_e32 v144, v144
	v_fma_f32 v144, v179, v189, -v144
	v_sin_f32_e32 v179, v144
	v_cos_f32_e32 v178, v144
	v_mul_f32_e32 v144, v180, v189
	v_floor_f32_e32 v144, v144
	v_fma_f32 v144, v180, v189, -v144
	v_sin_f32_e32 v184, v144
	v_cos_f32_e32 v185, v144
	v_mul_f32_e32 v144, v181, v189
	v_floor_f32_e32 v144, v144
	v_fma_f32 v144, v181, v189, -v144
	v_sin_f32_e32 v191, v144
	v_cos_f32_e32 v190, v144
	v_mul_f32_e32 v144, v182, v189
	v_floor_f32_e32 v144, v144
	v_fma_f32 v144, v182, v189, -v144
	v_sin_f32_e32 v192, v144
	v_cos_f32_e32 v193, v144
	v_mul_f32_e32 v144, v183, v189
	v_sin_f32_e32 v14, v15
	v_cos_f32_e32 v15, v15
	v_floor_f32_e32 v144, v144
	v_fma_f32 v144, v183, v189, -v144
	v_sin_f32_e32 v195, v144
	v_cos_f32_e32 v194, v144
	v_ashrrev_i32_e32 v189, 4, v186
	v_add_u32_e32 v207, 32, v189
	v_pk_add_f32 v[32:33], v[34:35], v[32:33]
	v_pk_mul_f32 v[34:35], v[82:83], v[82:83]
	v_lshlrev_b32_e32 v38, 5, v189
	v_pk_fma_f32 v[34:35], v[64:65], v[64:65], v[34:35]
	v_and_or_b32 v38, v38, s59, v39
	v_pk_add_f32 v[32:33], v[34:35], v[32:33]
	v_pk_mul_f32 v[34:35], v[96:97], v[96:97]
	v_lshlrev_b32_e32 v38, 1, v38
	v_pk_fma_f32 v[34:35], v[78:79], v[78:79], v[34:35]
	v_lshl_or_b32 v228, v36, 9, v38
	v_pk_add_f32 v[32:33], v[34:35], v[32:33]
	v_pk_mul_f32 v[34:35], v[108:109], v[108:109]
	v_lshrrev_b32_e32 v36, 1, v207
	v_pk_fma_f32 v[34:35], v[104:105], v[104:105], v[34:35]
	v_and_or_b32 v36, v36, s58, v37
	v_lshlrev_b32_e32 v82, 4, v186
	v_add_u32_e32 v108, 0, v228
	v_pk_add_f32 v[32:33], v[34:35], v[32:33]
	v_pk_mul_f32 v[34:35], v[116:117], v[116:117]
	v_lshl_or_b32 v229, v36, 9, v38
	v_lshlrev_b32_e32 v36, 8, v189
	v_and_b32_e32 v38, 0xf0, v186
	v_lshlrev_b32_e32 v39, 8, v207
	v_pk_fma_f32 v[34:35], v[112:113], v[112:113], v[34:35]
	v_add_u32_e32 v83, 0, v221
	v_pk_add_f32 v[32:33], v[34:35], v[32:33]
	v_pk_mul_f32 v[34:35], v[124:125], v[124:125]
	v_add_u32_e32 v109, 0, v229
	v_pk_fma_f32 v[34:35], v[122:123], v[122:123], v[34:35]
	v_pk_mul_f32 v[78:79], v[126:127], v[126:127]
	v_pk_add_f32 v[32:33], v[34:35], v[32:33]
	v_pk_mul_f32 v[34:35], v[100:101], v[100:101]
	s_mov_b32 s78, -1
	v_pk_fma_f32 v[34:35], v[98:99], v[98:99], v[34:35]
	v_mov_b32_e32 v219, 0
	v_pk_add_f32 v[32:33], v[34:35], v[32:33]
	v_pk_mul_f32 v[34:35], v[110:111], v[110:111]
	s_waitcnt vmcnt(3)
; __device__ __forceinline__ unsigned cvtpk(float lo, float hi) { unsigned r; asm volatile("v_cvt_pk_bf16_f32 %0, %1, %2" : "=v"(r) : "v"(lo), "v"(hi)); return r; }
; __device__ __forceinline__ float sin_rev(float rev) { return __builtin_amdgcn_sinf(rev); }
; __device__ __forceinline__ float cos_rev(float rev) { return __builtin_amdgcn_cosf(rev); }
; __device__ __forceinline__ int v_st_nat(int k, int c) { return ((k >> 3) * 4 + (c >> 5)) * 512 + ((k & 7) * 32 + (c & 31)) * 2; }
; __device__ __forceinline__ int v_rd_base(int lane) { return ((lane & 3) << 3) | (((lane >> 2) & 3) << 6) | (((lane >> 4) & 1) << 5) | (((lane >> 5) & 1) << 8); }
; #define SLOAD(k0) do { sr_.vs0 = *(const bf16x8*)(&Vh[(long)((k0) + sr) * LDK + sc]); sr_.vs1 = *(const bf16x8*)(&Vh[(long)((k0) + 32 + sr) * LDK + sc]); \
;     sr_.ks0 = *(const bf16x8*)(&Kh[(long)((k0) + sr) * LDK + sc]); sr_.ks1 = *(const bf16x8*)(&Kh[(long)((k0) + 32 + sr) * LDK + sc]); } while (0)
; __device__ __forceinline__ void attn_item(const bf16_t* __restrict__ Qb, const bf16_t* __restrict__ Kh, const bf16_t* __restrict__ Vh, const bf16_t* __restrict__ Zb, ...
;     ...
;         const int fi = (d1 & 1) * 16 + hq * 8 + e; float rev = pos * (__builtin_amdgcn_exp2f(-(float)fi * (13.287712379549449f / 32.0f)) * 0.15915494309189535f); rev -= floorf(rev);
;         const float sn = sin_rev(rev), cs = cos_rev(rev), y1 = x1 * rstd * ga, y2 = x2 * rstd * gb; o1[e] = y1 * cs - y2 * sn; o2[e] = y2 * cs + y1 * sn; }
; #pragma unroll
;       for (int e = 0; e < 8; ++e) qn2 += o1[e] * o1[e] + o2[e] * o2[e];
;       u32x4 p1 = {cvtpk(o1[0], o1[1]), cvtpk(o1[2], o1[3]), cvtpk(o1[4], o1[5]), cvtpk(o1[6], o1[7])}, p2 = {cvtpk(o2[0], o2[1]), cvtpk(o2[2], o2[3]), cvtpk(o2[4], o2[5]), cvtpk(o2[6], o2[7])};
;       qr[d1] = *reinterpret_cast<bf16x8*>(&p1); qr[d2] = *reinterpret_cast<bf16x8*>(&p2); }
;   }
;   const int sr = tid >> 4, sc = (tid & 15) * 8, vst0 = v_st_nat(sr, sc), vst1 = v_st_nat(32 + sr, sc), kst0 = KOFF + KSWZ(sr, sc * 2), kst1 = KOFF + KSWZ(32 + sr, sc * 2);
;   const int vb0 = (int)(uintptr_t)lds + v_rd_base(lane);
;   struct { bf16x8 vs0, vs1, ks0, ks1; } sr_;
;     ...
;   f32x16 pA0, pA1, pB0, pB1; float alA, alB; VF8 vfa; bf16x8 pa0, pa1, pa2, pa3; const int NT = seq / KVBLK;
;   int s_prev = 0, s_cur = SLOT, s_next = 2 * SLOT;
;   SLOAD(0); SWAIT(); SWRITE(0); __syncthreads();
	v_mov_b32_e32 v144, v2
	s_waitcnt vmcnt(2)
	v_mov_b32_e32 v145, v6
	v_pk_mul_f32 v[144:145], v[76:77], v[144:145]
	v_mov_b32_e32 v76, v15
	v_mov_b32_e32 v77, v14
	v_mul_f32_e32 v2, v14, v145
	v_pk_fma_f32 v[76:77], v[76:77], v[144:145], v[2:3] op_sel_hi:[1,1,0] neg_lo:[0,0,1] neg_hi:[0,0,1]
	v_mul_f32_e32 v2, v15, v145
	v_pk_fma_f32 v[144:145], v[14:15], v[144:145], v[2:3] op_sel_hi:[1,1,0]
	v_pk_mul_f32 v[14:15], v[0:1], v[60:61] op_sel_hi:[0,1]
	v_mov_b32_e32 v6, v3
	v_pk_mul_f32 v[2:3], v[14:15], v[6:7]
	v_pk_fma_f32 v[34:35], v[106:107], v[106:107], v[34:35]
	v_mul_f32_e32 v6, v147, v3
	v_pk_fma_f32 v[60:61], v[146:147], v[2:3], v[6:7] op_sel_hi:[1,1,0] neg_lo:[0,0,1] neg_hi:[0,0,1]
	v_mov_b32_e32 v6, v147
	v_mov_b32_e32 v7, v146
	v_mul_f32_e32 v14, v146, v3
	v_pk_fma_f32 v[146:147], v[6:7], v[2:3], v[14:15] op_sel_hi:[1,1,0]
	v_pk_mul_f32 v[2:3], v[0:1], v[74:75] op_sel_hi:[0,1]
	v_mov_b32_e32 v6, v4
	v_mov_b32_e32 v7, v8
	v_pk_mul_f32 v[2:3], v[2:3], v[6:7]
	v_mov_b32_e32 v6, v177
	v_mov_b32_e32 v7, v176
	v_mul_f32_e32 v4, v176, v3
	v_pk_fma_f32 v[74:75], v[6:7], v[2:3], v[4:5] op_sel_hi:[1,1,0] neg_lo:[0,0,1] neg_hi:[0,0,1]
	v_mul_f32_e32 v4, v177, v3
	v_pk_fma_f32 v[180:181], v[176:177], v[2:3], v[4:5] op_sel_hi:[1,1,0]
	v_pk_mul_f32 v[2:3], v[0:1], v[66:67] op_sel_hi:[0,1]
	v_mov_b32_e32 v8, v5
	v_pk_mul_f32 v[2:3], v[2:3], v[8:9]
	s_waitcnt vmcnt(0)
	v_mov_b32_e32 v15, v174
	v_mul_f32_e32 v4, v179, v3
	v_pk_fma_f32 v[66:67], v[178:179], v[2:3], v[4:5] op_sel_hi:[1,1,0] neg_lo:[0,0,1] neg_hi:[0,0,1]
	v_mov_b32_e32 v4, v179
	v_mov_b32_e32 v5, v178
	v_mul_f32_e32 v6, v178, v3
	v_pk_fma_f32 v[182:183], v[4:5], v[2:3], v[6:7] op_sel_hi:[1,1,0]
	v_pk_mul_f32 v[2:3], v[0:1], v[72:73] op_sel_hi:[0,1]
	v_mov_b32_e32 v4, v10
	v_mov_b32_e32 v5, v172
	v_pk_mul_f32 v[6:7], v[0:1], v[62:63] op_sel_hi:[0,1]
	v_mov_b32_e32 v172, v11
	v_pk_mul_f32 v[2:3], v[2:3], v[4:5]
	v_mov_b32_e32 v4, v185
	v_mov_b32_e32 v5, v184
	v_pk_mul_f32 v[6:7], v[6:7], v[172:173]
	v_mov_b32_e32 v10, v191
	v_mov_b32_e32 v11, v190
	v_pk_mul_f32 v[62:63], v[0:1], v[70:71] op_sel_hi:[0,1]
	v_mov_b32_e32 v174, v13
	v_pk_mul_f32 v[4:5], v[4:5], v[2:3]
	v_pk_mul_f32 v[8:9], v[190:191], v[6:7]
	v_pk_mul_f32 v[6:7], v[10:11], v[6:7]
	v_pk_mul_f32 v[10:11], v[0:1], v[68:69] op_sel_hi:[0,1]
	v_mov_b32_e32 v14, v12
	v_pk_mul_f32 v[12:13], v[62:63], v[174:175]
	v_mov_b32_e32 v62, v195
	v_mov_b32_e32 v63, v194
	v_pk_mul_f32 v[2:3], v[184:185], v[2:3]
	v_pk_mul_f32 v[10:11], v[10:11], v[14:15]
	v_mov_b32_e32 v14, v193
	v_mov_b32_e32 v15, v192
	v_pk_mul_f32 v[68:69], v[194:195], v[12:13]
	v_pk_mul_f32 v[12:13], v[62:63], v[12:13]
	v_mov_b32_e32 v62, v8
	v_mov_b32_e32 v63, v4
	v_mov_b32_e32 v4, v9
	v_pk_mul_f32 v[14:15], v[14:15], v[10:11]
	v_pk_add_f32 v[62:63], v[62:63], v[4:5] neg_lo:[0,1] neg_hi:[0,1]
	v_mov_b32_e32 v4, v6
	v_mov_b32_e32 v5, v2
	v_mov_b32_e32 v2, v7
	v_pk_mul_f32 v[10:11], v[192:193], v[10:11]
	v_pk_add_f32 v[72:73], v[4:5], v[2:3]
	v_mov_b32_e32 v2, v68
	v_mov_b32_e32 v3, v14
	v_mov_b32_e32 v14, v69
	v_pk_add_f32 v[68:69], v[2:3], v[14:15] neg_lo:[0,1] neg_hi:[0,1]
	v_mov_b32_e32 v2, v12
	v_mov_b32_e32 v3, v10
	v_mov_b32_e32 v10, v13
	v_and_b32_e32 v70, 0x78, v206
	v_mov_b32_e32 v71, v1
	v_pk_add_f32 v[184:185], v[2:3], v[10:11]
	v_mad_i64_i32 v[2:3], s[36:37], v189, s61, v[70:71]
	v_lshl_add_u64 v[2:3], v[2:3], 1, s[0:1]
	v_cvt_pk_bf16_f32 v176, v76, v60
	v_cvt_pk_bf16_f32 v177, v74, v66
	v_cvt_pk_bf16_f32 v178, v63, v62
	v_cvt_pk_bf16_f32 v179, v69, v68
	v_cvt_pk_bf16_f32 v172, v144, v146
	v_cvt_pk_bf16_f32 v173, v180, v182
	v_cvt_pk_bf16_f32 v174, v73, v72
	v_cvt_pk_bf16_f32 v175, v185, v184
	global_load_dwordx4 v[190:193], v[2:3], off offset:2560
	v_mad_i64_i32 v[4:5], s[36:37], v207, s61, v[70:71]
	v_lshl_add_u64 v[4:5], v[4:5], 1, s[0:1]
	global_load_dwordx4 v[194:197], v[4:5], off offset:2560
	global_load_dwordx4 v[198:201], v[2:3], off offset:2048
	global_load_dwordx4 v[202:205], v[4:5], off offset:2048
	v_lshlrev_b32_e32 v37, 1, v70
	s_waitcnt vmcnt(0)
	v_bitop3_b32 v231, v37, v36, v38 bitop3:0xde
	v_bitop3_b32 v232, v39, v37, v38 bitop3:0xf6
	v_add_u32_e32 v112, 0, v231
	v_add_u32_e32 v113, 0, v232
	v_pk_add_f32 v[56:57], v[34:35], v[32:33]
	v_and_b32_e32 v0, 0x3fffffc0, v186
	v_mov_b32_e32 v14, v1
	v_mov_b32_e32 v15, v1
	v_lshl_add_u32 v213, v0, 2, s56
	v_mov_b32_e32 v0, v1
	v_mov_b32_e32 v2, v1
	v_mov_b32_e32 v3, v1
	v_mov_b32_e32 v4, v1
	v_mov_b32_e32 v5, v1
	v_mov_b32_e32 v6, v1
	v_mov_b32_e32 v7, v1
	v_mov_b32_e32 v8, v1
	v_mov_b32_e32 v9, v1
	v_mov_b32_e32 v10, v1
	v_mov_b32_e32 v11, v1
	v_mov_b32_e32 v12, v1
	v_mov_b32_e32 v13, v1
	v_or_b32_e32 v106, 0xc0, v212
	v_or_b32_e32 v107, 0xe0, v212
	v_lshl_add_u32 v220, v187, 2, v213
	s_waitcnt vmcnt(3)
	ds_write_b128 v108, v[190:193]
	v_and_b32_e32 v190, 0xf0, v82
	v_bitop3_b32 v234, v188, v190, 16 bitop3:0x6c
	v_add_u32_e32 v36, v83, v234
	s_waitcnt vmcnt(2)
	ds_write_b128 v109, v[194:197]
	s_waitcnt vmcnt(1)
	ds_write_b128 v112, v[198:201] offset:16384
	s_waitcnt vmcnt(0)
	ds_write_b128 v113, v[202:205] offset:16384
	s_waitcnt lgkmcnt(0)
	s_barrier
; #define SLOAD(k0) do { sr_.vs0 = *(const bf16x8*)(&Vh[(long)((k0) + sr) * LDK + sc]); sr_.vs1 = *(const bf16x8*)(&Vh[(long)((k0) + 32 + sr) * LDK + sc]); \
;     sr_.ks0 = *(const bf16x8*)(&Kh[(long)((k0) + sr) * LDK + sc]); sr_.ks1 = *(const bf16x8*)(&Kh[(long)((k0) + 32 + sr) * LDK + sc]); } while (0)
; __device__ __forceinline__ void qkt(f32x16& p0, f32x16& p1, const bf16_t* Ks, const bf16x8* qr, const f32x16& negm, int r32, int hi) {
; #pragma unroll
;   for (int d0 = 0; d0 < 8; ++d0) { int cb = (d0 * 16 + hi * 8) * 2;
;     bf16x8 b0 = *reinterpret_cast<const bf16x8*>((const char*)Ks + KSWZ(r32, cb));
;     bf16x8 b1 = *reinterpret_cast<const bf16x8*>((const char*)Ks + KSWZ(32 + r32, cb));
;     if (d0 == 0) { p0 = __builtin_amdgcn_mfma_f32_32x32x16_bf16(b0, qr[0], negm, 0, 0, 0); p1 = __builtin_amdgcn_mfma_f32_32x32x16_bf16(b1, qr[0], negm, 0, 0, 0); }
;     else { p0 = __builtin_amdgcn_mfma_f32_32x32x16_bf16(b0, qr[d0], p0, 0, 0, 0); p1 = __builtin_amdgcn_mfma_f32_32x32x16_bf16(b1, qr[d0], p1, 0, 0, 0); } }
; }
; __device__ __forceinline__ void attn_item(const bf16_t* __restrict__ Qb, const bf16_t* __restrict__ Kh, const bf16_t* __restrict__ Vh, const bf16_t* __restrict__ Zb, ...
;     ...
;   SLOAD(KVBLK);
;   qkt(pA0, pA1, (const bf16_t*)(lds + KOFF), qr, negm, r32, hi); partialSM<true>(pA0, pA1, m_reg, negm, alA);
	ds_read_b128 v[48:51], v36 offset:24576
	ds_read_b128 v[52:55], v36 offset:16384
	s_waitcnt lgkmcnt(0)
	v_mfma_f32_32x32x16_bf16 v[32:47], v[52:55], v[152:155], v[16:31]
	v_fma_f32 v52, v114, v114, v58
	v_fma_f32 v53, v115, v115, v59
	v_bitop3_b32 v233, v212, v190, 32 bitop3:0x36
	v_add_f32_e64 v64, v52, v56
	v_add_f32_e64 v65, v53, v57
	v_add_u32_e32 v56, v83, v233
	ds_read_b128 v[52:55], v56 offset:24576
	ds_read_b128 v[56:59], v56 offset:16384
	v_bitop3_b32 v230, v212, v190, 64 bitop3:0x36
	v_bitop3_b32 v227, v212, v190, s62 bitop3:0x36
	v_mfma_f32_32x32x16_bf16 v[16:31], v[48:51], v[152:155], v[16:31]
	v_fma_f32 v48, v118, v118, v78
	v_fma_f32 v49, v119, v119, v79
	v_mul_f32_e64 v50, v128, v128
	v_mul_f32_e64 v51, v129, v129
	v_add_f32_e64 v48, v48, v64
	v_add_f32_e64 v49, v49, v65
	v_pk_fma_f32 v[50:51], v[102:103], v[102:103], v[50:51]
	v_bitop3_b32 v226, v212, v190, s63 bitop3:0x36
	v_pk_add_f32 v[48:49], v[48:49], v[50:51]
	v_pk_mul_f32 v[50:51], v[130:131], v[130:131]
	s_waitcnt lgkmcnt(0)
	v_mfma_f32_32x32x16_bf16 v[32:47], v[56:59], v[160:163], v[32:47]
	v_fma_f32 v50, v94, v94, v50
	v_fma_f32 v51, v95, v95, v51
	v_add_u32_e32 v56, v83, v230
	v_add_f32_e64 v64, v50, v48
	v_add_f32_e64 v65, v51, v49
	v_pk_mul_f32 v[48:49], v[132:133], v[132:133]
	v_bitop3_b32 v225, v212, v190, s64 bitop3:0x36
	v_pk_fma_f32 v[78:79], v[92:93], v[92:93], v[48:49]
	ds_read_b128 v[48:51], v56 offset:24576
	ds_read_b128 v[56:59], v56 offset:16384
	v_mfma_f32_32x32x16_bf16 v[16:31], v[52:55], v[160:163], v[16:31]
	v_mul_f32_e64 v54, v134, v134
	v_mul_f32_e64 v55, v135, v135
	v_add_f32_e64 v52, v78, v64
	v_add_f32_e64 v53, v79, v65
	v_fma_f32 v54, v90, v90, v54
	v_fma_f32 v55, v91, v91, v55
	v_bitop3_b32 v224, v212, v190, s60 bitop3:0x36
	v_pk_add_f32 v[52:53], v[54:55], v[52:53]
	v_pk_mul_f32 v[54:55], v[136:137], v[136:137]
	v_bitop3_b32 v223, v212, v190, s59 bitop3:0x36
	v_pk_fma_f32 v[54:55], v[88:89], v[88:89], v[54:55]
	s_waitcnt lgkmcnt(0)
	v_mfma_f32_32x32x16_bf16 v[32:47], v[56:59], v[148:151], v[32:47]
	v_add_f32_e64 v52, v54, v52
	v_add_f32_e64 v53, v55, v53
	v_mul_f32_e64 v54, v138, v138
	v_mul_f32_e64 v55, v139, v139
	v_add_u32_e32 v56, v83, v227
	v_pk_fma_f32 v[54:55], v[86:87], v[86:87], v[54:55]
	v_bitop3_b32 v236, v212, v221, v190 bitop3:0xde
	v_pk_add_f32 v[64:65], v[54:55], v[52:53]
	ds_read_b128 v[52:55], v56 offset:24576
	ds_read_b128 v[56:59], v56 offset:16384
	v_mfma_f32_32x32x16_bf16 v[16:31], v[48:51], v[148:151], v[16:31]
	v_mul_f32_e64 v48, v140, v140
	v_mul_f32_e64 v49, v141, v141
	v_mul_f32_e64 v50, v142, v142
	v_mul_f32_e64 v51, v143, v143
	v_fma_f32 v48, v84, v84, v48
	v_fma_f32 v49, v85, v85, v49
	v_pk_fma_f32 v[50:51], v[80:81], v[80:81], v[50:51]
	v_pk_add_f32 v[48:49], v[48:49], v[64:65]
	v_bitop3_b32 v242, v106, v221, v190 bitop3:0xde
	v_pk_add_f32 v[48:49], v[50:51], v[48:49]
	s_waitcnt lgkmcnt(0)
	v_mfma_f32_32x32x16_bf16 v[32:47], v[56:59], v[156:159], v[32:47]
	v_mul_f32_e64 v50, v144, v144
	v_mul_f32_e64 v51, v145, v145
	v_add_u32_e32 v56, v83, v226
	v_fma_f32 v50, v76, v76, v50
	v_fma_f32 v51, v77, v77, v51
	v_pk_mul_f32 v[76:77], v[146:147], v[146:147]
	v_pk_add_f32 v[64:65], v[48:49], v[50:51]
	ds_read_b128 v[48:51], v56 offset:24576
	ds_read_b128 v[56:59], v56 offset:16384
	v_bitop3_b32 v243, v107, v221, v190 bitop3:0xde
	v_mfma_f32_32x32x16_bf16 v[16:31], v[52:55], v[156:159], v[16:31]
	v_fma_f32 v52, v60, v60, v76
	v_fma_f32 v53, v61, v61, v77
	v_mul_f32_e64 v54, v180, v180
	v_mul_f32_e64 v55, v181, v181
	v_add_f32_e64 v52, v52, v64
	v_add_f32_e64 v53, v53, v65
	v_pk_fma_f32 v[54:55], v[74:75], v[74:75], v[54:55]
	s_nop 0
	v_pk_add_f32 v[52:53], v[54:55], v[52:53]
	v_pk_mul_f32 v[54:55], v[182:183], v[182:183]
	s_waitcnt lgkmcnt(0)
	v_mfma_f32_32x32x16_bf16 v[32:47], v[56:59], v[168:171], v[32:47]
	v_fma_f32 v54, v66, v66, v54
	v_fma_f32 v55, v67, v67, v55
	v_add_u32_e32 v56, v83, v225
	v_add_f32_e64 v60, v54, v52
	v_add_f32_e64 v61, v55, v53
	v_pk_mul_f32 v[52:53], v[72:73], v[72:73]
	s_nop 0
	v_pk_fma_f32 v[62:63], v[62:63], v[62:63], v[52:53]
	ds_read_b128 v[52:55], v56 offset:24576
	ds_read_b128 v[56:59], v56 offset:16384
	v_mfma_f32_32x32x16_bf16 v[16:31], v[48:51], v[168:171], v[16:31]
	v_add_f32_e64 v48, v63, v60
	v_add_f32_e64 v49, v62, v61
	v_mul_f32_e64 v50, v184, v184
	v_mul_f32_e64 v51, v185, v185
	v_add_f32_e64 v48, v62, v48
	v_add_f32_e64 v49, v63, v49
	v_pk_fma_f32 v[50:51], v[68:69], v[68:69], v[50:51]
	v_lshlrev_b32_e32 v60, 3, v208
	v_pk_add_f32 v[48:49], v[50:51], v[48:49] op_sel:[1,0] op_sel_hi:[0,1]
	v_pk_add_f32 v[64:65], v[50:51], v[48:49]
	s_waitcnt lgkmcnt(0)
	v_mfma_f32_32x32x16_bf16 v[32:47], v[56:59], v[176:179], v[32:47]
	v_and_b32_e32 v48, 0xc0, v82
	v_add_u32_e32 v56, v83, v224
	v_and_or_b32 v61, v60, 24, v48
	v_lshlrev_b32_e32 v62, 1, v186
	ds_read_b128 v[48:51], v56 offset:24576
	ds_read_b128 v[56:59], v56 offset:16384
	v_or_b32_e32 v65, 0xa0, v212
	v_bitop3_b32 v241, v65, v221, v190 bitop3:0xde
	v_mfma_f32_32x32x16_bf16 v[16:31], v[52:55], v[176:179], v[16:31]
	v_and_b32_e32 v52, 32, v62
	v_and_b32_e32 v53, 0x100, v60
	v_or3_b32 v52, v61, v52, v53
	v_add_u32_e32 v235, s6, v52
	v_add_u32_e32 v52, 64, v189
	v_mad_i64_i32 v[52:53], s[6:7], v52, s61, v[70:71]
	v_add_u32_e32 v62, 0x60, v189
	s_waitcnt lgkmcnt(0)
	v_mfma_f32_32x32x16_bf16 v[32:47], v[56:59], v[164:167], v[32:47]
	v_lshl_add_u64 v[60:61], v[52:53], 1, s[0:1]
	v_add_u32_e32 v56, v83, v223
	ds_read_b128 v[52:55], v56 offset:24576
	ds_read_b128 v[56:59], v56 offset:16384
	v_mfma_f32_32x32x16_bf16 v[16:31], v[48:51], v[164:167], v[16:31]
	v_mad_i64_i32 v[48:49], s[6:7], v62, s61, v[70:71]
	v_lshl_add_u64 v[66:67], v[48:49], 1, s[0:1]
	global_load_dwordx4 v[48:51], v[60:61], off offset:2560
	s_nop 0
	global_load_dwordx4 v[60:63], v[60:61], off offset:2048
	s_nop 0
	global_load_dwordx4 v[98:101], v[66:67], off offset:2560
	global_load_dwordx4 v[102:105], v[66:67], off offset:2048
	v_cmp_gt_u32_e64 s[6:7], 32, v208
	s_waitcnt lgkmcnt(0)
; template <bool FIRST, bool DOEXP = true>
; __device__ __forceinline__ void partialSM(f32x16& p0, f32x16& p1, float& m_reg, f32x16& negm, float& alpha, const bool track = true) {
;   if (!FIRST && !track) { alpha = 1.f;
;     if (DOEXP) {
; #pragma unroll
;       for (int r = 0; r < 16; ++r) p0[r] = __builtin_amdgcn_exp2f(p0[r]); }
;     return; }
;   float pmax = p0[0];
; #pragma unroll
;   for (int r = 1; r < 16; ++r) pmax = fmaxf(pmax, p0[r]);
; #pragma unroll
;   for (int r = 0; r < 16; ++r) pmax = fmaxf(pmax, p1[r]);
;   { auto rr = __builtin_amdgcn_permlane32_swap(__float_as_uint(pmax), __float_as_uint(pmax), false, false);
;     pmax = fmaxf(__uint_as_float(rr[0]), __uint_as_float(rr[1])); }
;   if (!FIRST && __builtin_expect(__all(pmax <= THRL), 1)) { alpha = 1.f; }
;   else { const float dl = FIRST ? pmax : fmaxf(pmax, 0.f); m_reg += dl; alpha = FIRST ? 1.f : __builtin_amdgcn_exp2f(-dl);
; #pragma unroll
;     for (int r = 0; r < 16; ++r) { p0[r] -= dl; p1[r] -= dl; }
; #pragma unroll
;     for (int r = 0; r < 16; ++r) negm[r] = -m_reg;
;     asm volatile("" : "+v"(negm)); }
;   if (DOEXP) {
; #pragma unroll
;     for (int r = 0; r < 16; ++r) p0[r] = __builtin_amdgcn_exp2f(p0[r]); }
; __device__ __forceinline__ void attn_item(const bf16_t* __restrict__ Qb, const bf16_t* __restrict__ Kh, const bf16_t* __restrict__ Vh, const bf16_t* __restrict__ Zb, ...
;     ...
;   qkt(pA0, pA1, (const bf16_t*)(lds + KOFF), qr, negm, r32, hi); partialSM<true>(pA0, pA1, m_reg, negm, alA);
;   { auto rr = __builtin_amdgcn_permlane32_swap(__float_as_uint(qn2), __float_as_uint(qn2), false, false); qn2 = __uint_as_float(rr[0]) + __uint_as_float(rr[1]); }
;   const bool track = !__all(__builtin_sqrtf(qn2) * kmaxg - m_reg <= 90.f);
	v_mfma_f32_32x32x16_bf16 v[32:47], v[56:59], v[172:175], v[32:47]
	v_or_b32_e32 v56, 32, v212
	v_or_b32_e32 v57, 64, v212
	v_or_b32_e32 v58, 0x60, v212
	v_or_b32_e32 v59, 0x80, v212
	v_bitop3_b32 v237, v56, v221, v190 bitop3:0xde
	v_bitop3_b32 v238, v57, v221, v190 bitop3:0xde
	v_bitop3_b32 v239, v58, v221, v190 bitop3:0xde
	v_mfma_f32_32x32x16_bf16 v[16:31], v[52:55], v[172:175], v[16:31]
	s_nop 3
	v_max_f32_e32 v52, v33, v33
	v_max_f32_e32 v53, v32, v32
	v_max_f32_e32 v52, v53, v52
	v_max3_f32 v52, v52, v34, v35
	v_max3_f32 v52, v52, v36, v37
	v_max3_f32 v52, v52, v38, v39
	v_max3_f32 v52, v52, v40, v41
	v_max3_f32 v52, v52, v42, v43
	v_max3_f32 v52, v52, v44, v45
	v_max3_f32 v52, v52, v46, v47
	v_max3_f32 v52, v52, v16, v17
	v_max3_f32 v52, v52, v18, v19
	v_max3_f32 v52, v52, v20, v21
	v_max3_f32 v52, v52, v22, v23
	v_max3_f32 v52, v52, v24, v25
	v_max3_f32 v52, v52, v26, v27
	v_max3_f32 v52, v52, v28, v29
	v_max3_f32 v52, v52, v30, v31
	v_mov_b32_e32 v53, v52
	s_nop 1
	v_permlane32_swap_b32_e32 v52, v53
	v_max_f32_e32 v53, v53, v53
	v_max_f32_e32 v52, v52, v52
	v_max_f32_e32 v52, v52, v53
	v_sub_f32_e32 v82, v16, v52
	v_mov_b32_e32 v16, v64
	s_nop 1
	v_permlane32_swap_b32_e32 v64, v16
	v_add_f32_e32 v16, v64, v16
	v_sub_f32_e32 v83, v17, v52
	v_mul_f32_e32 v17, 0x4f800000, v16
	v_cmp_gt_f32_e32 vcc, s65, v16
	v_sub_f32_e32 v84, v18, v52
	v_sub_f32_e32 v85, v19, v52
	v_cndmask_b32_e32 v16, v16, v17, vcc
	v_sqrt_f32_e32 v17, v16
	v_add_f32_e32 v222, 0, v52
	v_sub_f32_e32 v32, v32, v52
	v_sub_f32_e32 v33, v33, v52
	v_add_u32_e32 v18, -1, v17
	v_fma_f32 v19, -v18, v17, v16
	v_cmp_ge_f32_e64 s[0:1], 0, v19
	v_add_u32_e32 v19, 1, v17
	v_sub_f32_e32 v34, v34, v52
	v_cndmask_b32_e64 v18, v17, v18, s[0:1]
	v_fma_f32 v17, -v19, v17, v16
	v_cmp_lt_f32_e64 s[0:1], 0, v17
	v_sub_f32_e32 v35, v35, v52
	v_sub_f32_e32 v36, v36, v52
	v_cndmask_b32_e64 v17, v18, v19, s[0:1]
	v_mul_f32_e32 v18, 0x37800000, v17
	v_cndmask_b32_e32 v17, v17, v18, vcc
	v_cmp_class_f32_e32 vcc, v16, v218
	v_sub_f32_e32 v37, v37, v52
	v_sub_f32_e32 v38, v38, v52
	v_cndmask_b32_e32 v16, v17, v16, vcc
	v_fma_f32 v16, v216, v16, -v222
	v_cmp_ge_f32_e32 vcc, s66, v16
	s_cmp_lg_u64 vcc, exec
	s_cselect_b64 s[0:1], -1, 0
	s_or_b32 s8, s9, s8
	v_sub_f32_e32 v39, v39, v52
	v_sub_f32_e32 v40, v40, v52
	v_sub_f32_e32 v41, v41, v52
	v_sub_f32_e32 v42, v42, v52
	v_sub_f32_e32 v43, v43, v52
	v_sub_f32_e32 v44, v44, v52
	v_sub_f32_e32 v45, v45, v52
	v_sub_f32_e32 v46, v46, v52
	v_sub_f32_e32 v47, v47, v52
	v_xor_b32_e32 v66, 0x80000000, v222
	v_mov_b32_e32 v16, s8
	v_mov_b32_e32 v17, v1
	v_and_b32_e32 v18, 15, v186
	v_mov_b32_e32 v67, v66
	v_mov_b32_e32 v68, v66
	v_mov_b32_e32 v69, v66
	v_mov_b32_e32 v70, v66
	v_mov_b32_e32 v71, v66
	v_mov_b32_e32 v72, v66
	v_mov_b32_e32 v73, v66
	v_mov_b32_e32 v74, v66
	v_mov_b32_e32 v75, v66
	v_mov_b32_e32 v76, v66
	v_mov_b32_e32 v77, v66
	v_mov_b32_e32 v78, v66
	v_mov_b32_e32 v79, v66
	v_mov_b32_e32 v80, v66
	v_mov_b32_e32 v81, v66
	v_exp_f32_e32 v114, v32
	v_exp_f32_e32 v115, v33
	v_exp_f32_e32 v116, v34
	v_exp_f32_e32 v117, v35
	v_exp_f32_e32 v118, v36
	v_exp_f32_e32 v119, v37
	v_exp_f32_e32 v120, v38
	v_exp_f32_e32 v121, v39
	v_exp_f32_e32 v122, v40
	v_exp_f32_e32 v123, v41
	v_exp_f32_e32 v124, v42
	v_exp_f32_e32 v125, v43
	v_exp_f32_e32 v126, v44
	v_exp_f32_e32 v127, v45
	v_exp_f32_e32 v128, v46
	v_exp_f32_e32 v129, v47
	v_mad_i64_i32 v[16:17], s[8:9], v189, s51, v[16:17]
	v_lshlrev_b32_e32 v18, 4, v18
	v_mov_b32_e32 v19, v1
	v_sub_f32_e32 v97, v31, v52
	v_sub_f32_e32 v96, v30, v52
	v_sub_f32_e32 v95, v29, v52
	v_sub_f32_e32 v94, v28, v52
	v_sub_f32_e32 v93, v27, v52
	v_sub_f32_e32 v92, v26, v52
	v_sub_f32_e32 v91, v25, v52
	v_sub_f32_e32 v90, v24, v52
	v_sub_f32_e32 v89, v23, v52
	v_sub_f32_e32 v88, v22, v52
	v_sub_f32_e32 v87, v21, v52
	v_sub_f32_e32 v86, v20, v52
	s_waitcnt vmcnt(0)
; __device__ __forceinline__ int v_st_nat(int k, int c) { return ((k >> 3) * 4 + (c >> 5)) * 512 + ((k & 7) * 32 + (c & 31)) * 2; }
; __device__ __forceinline__ int v_rd_base(int lane) { return ((lane & 3) << 3) | (((lane >> 2) & 3) << 6) | (((lane >> 4) & 1) << 5) | (((lane >> 5) & 1) << 8); }
; #define SLOAD(k0) do { sr_.vs0 = *(const bf16x8*)(&Vh[(long)((k0) + sr) * LDK + sc]); sr_.vs1 = *(const bf16x8*)(&Vh[(long)((k0) + 32 + sr) * LDK + sc]); \
;     sr_.ks0 = *(const bf16x8*)(&Kh[(long)((k0) + sr) * LDK + sc]); sr_.ks1 = *(const bf16x8*)(&Kh[(long)((k0) + 32 + sr) * LDK + sc]); } while (0)
; #define SWRITE(so) do { *(bf16x8*)(lds + (so) + vst0) = sr_.vs0; *(bf16x8*)(lds + (so) + vst1) = sr_.vs1;          \
;     *(bf16x8*)(lds + (so) + kst0) = sr_.ks0; *(bf16x8*)(lds + (so) + kst1) = sr_.ks1; } while (0)
; #define SWAIT() asm volatile("s_waitcnt vmcnt(0)" ::: "memory")
; __device__ __forceinline__ void attn_item(const bf16_t* __restrict__ Qb, const bf16_t* __restrict__ Kh, const bf16_t* __restrict__ Vh, const bf16_t* __restrict__ Zb, ...
;     ...
;   const int sr = tid >> 4, sc = (tid & 15) * 8, vst0 = v_st_nat(sr, sc), vst1 = v_st_nat(32 + sr, sc), kst0 = KOFF + KSWZ(sr, sc * 2), kst1 = KOFF + KSWZ(32 + sr, sc * 2);
;   const int vb0 = (int)(uintptr_t)lds + v_rd_base(lane);
;   struct { bf16x8 vs0, vs1, ks0, ks1; } sr_;
;     ...
;   f32x16 pA0, pA1, pB0, pB1; float alA, alB; VF8 vfa; bf16x8 pa0, pa1, pa2, pa3; const int NT = seq / KVBLK;
;   int s_prev = 0, s_cur = SLOT, s_next = 2 * SLOT;
;   SLOAD(0); SWAIT(); SWRITE(0); __syncthreads();
;   SLOAD(KVBLK);
;   qkt(pA0, pA1, (const bf16_t*)(lds + KOFF), qr, negm, r32, hi); partialSM<true>(pA0, pA1, m_reg, negm, alA);
;   { auto rr = __builtin_amdgcn_permlane32_swap(__float_as_uint(qn2), __float_as_uint(qn2), false, false); qn2 = __uint_as_float(rr[0]) + __uint_as_float(rr[1]); }
;   const bool track = !__all(__builtin_sqrtf(qn2) * kmaxg - m_reg <= 90.f);
;   SWAIT(); SWRITE(SLOT); __syncthreads();
	s_waitcnt vmcnt(3)
	ds_write_b128 v108, v[48:51] offset:32768
	s_waitcnt vmcnt(1)
	ds_write_b128 v109, v[98:101] offset:32768
	ds_write_b128 v112, v[60:63] offset:49152
	s_waitcnt vmcnt(0)
	ds_write_b128 v113, v[102:105] offset:49152
	v_bitop3_b32 v240, v59, v221, v190 bitop3:0xde
	v_lshl_add_u64 v[16:17], v[16:17], 0, v[18:19]
	v_mov_b64_e32 v[64:65], v[14:15]
	v_mov_b64_e32 v[48:49], v[14:15]
	v_mov_b64_e32 v[32:33], v[14:15]
	v_lshl_add_u64 v[214:215], s[20:21], 0, v[16:17]
	v_mov_b64_e32 v[62:63], v[12:13]
	v_mov_b64_e32 v[60:61], v[10:11]
	v_mov_b64_e32 v[58:59], v[8:9]
	v_mov_b64_e32 v[56:57], v[6:7]
	v_mov_b64_e32 v[54:55], v[4:5]
	v_mov_b64_e32 v[52:53], v[2:3]
	v_mov_b64_e32 v[50:51], v[0:1]
	v_mov_b64_e32 v[46:47], v[12:13]
	v_mov_b64_e32 v[44:45], v[10:11]
	v_mov_b64_e32 v[42:43], v[8:9]
	v_mov_b64_e32 v[40:41], v[6:7]
	v_mov_b64_e32 v[38:39], v[4:5]
	v_mov_b64_e32 v[36:37], v[2:3]
	v_mov_b64_e32 v[34:35], v[0:1]
	v_mov_b64_e32 v[30:31], v[12:13]
	v_mov_b64_e32 v[28:29], v[10:11]
	v_mov_b64_e32 v[26:27], v[8:9]
	v_mov_b64_e32 v[24:25], v[6:7]
	v_mov_b64_e32 v[22:23], v[4:5]
	v_mov_b64_e32 v[20:21], v[2:3]
	v_mov_b64_e32 v[18:19], v[0:1]
	v_mov_b64_e32 v[16:17], v[14:15]
	v_mov_b64_e32 v[14:15], v[12:13]
	v_mov_b64_e32 v[12:13], v[10:11]
	v_mov_b64_e32 v[10:11], v[8:9]
	v_mov_b64_e32 v[8:9], v[6:7]
	v_mov_b64_e32 v[6:7], v[4:5]
	v_mov_b64_e32 v[4:5], v[2:3]
	v_mov_b64_e32 v[2:3], v[0:1]
	v_add_co_u32_e32 v248, vcc, s67, v214
	s_nop 1
	v_addc_co_u32_e32 v249, vcc, -1, v215, vcc
	v_add_co_u32_e32 v250, vcc, s68, v214
	s_nop 1
	v_addc_co_u32_e32 v251, vcc, -1, v215, vcc
	global_load_dwordx4 v[180:183], v[248:249], off
	global_load_dwordx4 v[184:187], v[248:249], off offset:-512
	global_load_dwordx4 v[192:195], v[250:251], off
	global_load_dwordx4 v[188:191], v[250:251], off offset:-512
	v_add_u32_e32 v252, 0x10000, v228
	v_add_u32_e32 v253, 0x10000, v229
	v_add_u32_e32 v254, 0x10000, v231
	v_add_u32_e32 v255, 0x10000, v232
	s_waitcnt vmcnt(0)
	ds_write_b128 v252, v[180:183]
	ds_write_b128 v253, v[192:195]
	ds_write_b128 v254, v[184:187] offset:16384
	ds_write_b128 v255, v[188:191] offset:16384
	v_mbcnt_lo_u32_b32 v248, -1, 0
	v_mbcnt_hi_u32_b32 v248, -1, v248
	s_lshr_b32 s79, s33, 6
	s_lshl_b32 s100, s79, 10
	s_lshl_b32 s101, s79, 11
	s_mov_b32 s76, 0x82000
	s_mov_b32 s77, 0
	v_and_b32_e32 v249, 15, v248
	v_lshrrev_b32_e32 v250, 4, v248
	v_lshl_add_u32 v250, s79, 2, v250
	v_and_b32_e32 v251, 15, v250
	v_xor_b32_e32 v251, v249, v251
	v_sub_u32_e32 v251, v251, v249
	v_lshlrev_b32_e32 v251, 4, v251
	v_add_u32_e32 v252, 0xfffbee00, v251
	v_ashrrev_i32_e32 v253, 31, v252
	v_and_b32_e32 v254, 31, v248
	v_lshrrev_b32_e32 v254, 2, v254
	v_lshl_add_u32 v254, s79, 3, v254
	v_sub_u32_e32 v254, v254, v250
	v_add_u32_e32 v254, 0xffffffe0, v254
	v_mov_b32_e32 v255, 0x2080
	v_mul_lo_u32 v254, v254, v255
	v_lshrrev_b32_e32 v255, 5, v248
	v_lshl_add_u32 v254, v255, 6, v254
	v_and_b32_e32 v255, 3, v248
	v_lshl_add_u32 v254, v255, 4, v254
	v_lshlrev_b32_e32 v255, 4, v249
	v_sub_u32_e32 v254, v254, v255
	s_waitcnt lgkmcnt(0)
	v_lshl_add_u64 v[180:181], v[214:215], 0, v[252:253]
	v_ashrrev_i32_e32 v255, 31, v254
	v_add_co_u32_e32 v182, vcc, 0x41000, v180
	s_nop 1
	v_addc_co_u32_e32 v183, vcc, 0, v181, vcc
	v_lshl_add_u64 v[214:215], v[214:215], 0, v[254:255]
	s_mov_b32 s96, 0x8000
	s_mov_b32 s8, 0
	s_cmp_ge_u32 s33, 0x100
	s_cbranch_scc1 .Lh2_pro
	s_barrier

; #define SBAR() __builtin_amdgcn_sched_barrier(0)
; #define PVE_M(OD, PA, L, H, IDX) do { OD = __builtin_amdgcn_mfma_f32_32x32x16_bf16(PA, PKV(L, H), OD, 0, 0, 0); SBAR(); p[IDX] = __builtin_amdgcn_exp2f(p[IDX]); asm volatile("" : "+v"(p)); SBAR(); } while (0)
; __device__ __forceinline__ void pv_exp(f32x16* o, int vb, bf16x8 pa0, bf16x8 pa1, bf16x8 pa2, bf16x8 pa3, f32x16& p, VF8& fa) {
;   VF8 fb;
;   asm volatile("s_waitcnt lgkmcnt(0)" ::: "memory"); SBAR();
;   PVE_M(o[0], pa0, fa.l0, fa.h0, 0); PVE_M(o[0], pa1, fa.l1, fa.h1, 1); vf8_read<1>(fb, vb); SBAR(); PVE_M(o[0], pa2, fa.l2, fa.h2, 2); PVE_M(o[0], pa3, fa.l3, fa.h3, 3);
;   asm volatile("s_waitcnt lgkmcnt(0)" ::: "memory"); SBAR();
;   PVE_M(o[1], pa0, fb.l0, fb.h0, 4); PVE_M(o[1], pa1, fb.l1, fb.h1, 5); vf8_read<2>(fa, vb); SBAR(); PVE_M(o[1], pa2, fb.l2, fb.h2, 6); PVE_M(o[1], pa3, fb.l3, fb.h3, 7);
;   asm volatile("s_waitcnt lgkmcnt(0)" ::: "memory"); SBAR();
;   PVE_M(o[2], pa0, fa.l0, fa.h0, 8); PVE_M(o[2], pa1, fa.l1, fa.h1, 9); vf8_read<3>(fb, vb); SBAR(); PVE_M(o[2], pa2, fa.l2, fa.h2, 10); PVE_M(o[2], pa3, fa.l3, fa.h3, 11);
;   asm volatile("s_waitcnt lgkmcnt(0)" ::: "memory"); SBAR();
;   PVE_M(o[3], pa0, fb.l0, fb.h0, 12); PVE_M(o[3], pa1, fb.l1, fb.h1, 13); PVE_M(o[3], pa2, fb.l2, fb.h2, 14); PVE_M(o[3], pa3, fb.l3, fb.h3, 15);
; }
.LBB0_457:
	s_waitcnt vmcnt(0)
	s_barrier
	s_add_i32 s79, s98, s100
	s_add_i32 m0, s79, 0x4000
	s_add_i32 s79, s79, 0x6000
	global_load_lds_dwordx4 v[180:181], off
	s_mov_b32 m0, s79
	s_add_i32 s79, s98, s101
	global_load_lds_dwordx4 v[182:183], off
	s_mov_b32 m0, s79
	s_add_i32 s79, s79, 0x380
	global_load_lds_dwordx4 v[214:215], off
	s_mov_b32 m0, s79
	s_nop 0
	global_load_lds_dwordx4 v[214:215], off offset:128
	v_lshl_add_u64 v[180:181], v[180:181], 0, s[76:77]
	v_lshl_add_u64 v[182:183], v[182:183], 0, s[76:77]
	v_lshl_add_u64 v[214:215], v[214:215], 0, s[76:77]
	s_waitcnt lgkmcnt(0)
	v_mfma_f32_32x32x16_bf16 v[50:65], v[196:199], v[94:97], v[50:65]
	v_exp_f32_e32 v132, v132
	v_mfma_f32_32x32x16_bf16 v[50:65], v[204:207], v[90:93], v[50:65]
	v_exp_f32_e32 v133, v133
	ds_read_b64_tr_b16 v[90:91], v0 offset:0x200
	ds_read_b64_tr_b16 v[92:93], v0 offset:0xa00
	ds_read_b64_tr_b16 v[94:95], v0 offset:0x1200
	ds_read_b64_tr_b16 v[96:97], v0 offset:0x1a00
	ds_read_b64_tr_b16 v[114:115], v0 offset:0x2200
	ds_read_b64_tr_b16 v[116:117], v0 offset:0x2a00
	ds_read_b64_tr_b16 v[118:119], v0 offset:0x3200
	ds_read_b64_tr_b16 v[120:121], v0 offset:0x3a00
	v_mfma_f32_32x32x16_bf16 v[50:65], v[200:203], v[86:89], v[50:65]
	v_exp_f32_e32 v134, v134
	v_mfma_f32_32x32x16_bf16 v[50:65], v[208:211], v[82:85], v[50:65]
	v_exp_f32_e32 v135, v135
	s_waitcnt lgkmcnt(0)
	v_mfma_f32_32x32x16_bf16 v[34:49], v[196:199], v[90:93], v[34:49]
	v_exp_f32_e32 v136, v136
	v_mfma_f32_32x32x16_bf16 v[34:49], v[204:207], v[94:97], v[34:49]
	v_exp_f32_e32 v137, v137
	ds_read_b64_tr_b16 v[82:83], v0 offset:0x400
	ds_read_b64_tr_b16 v[84:85], v0 offset:0xc00
	ds_read_b64_tr_b16 v[86:87], v0 offset:0x1400
	ds_read_b64_tr_b16 v[88:89], v0 offset:0x1c00
	ds_read_b64_tr_b16 v[90:91], v0 offset:0x2400
	ds_read_b64_tr_b16 v[92:93], v0 offset:0x2c00
	ds_read_b64_tr_b16 v[94:95], v0 offset:0x3400
	ds_read_b64_tr_b16 v[96:97], v0 offset:0x3c00
	v_mfma_f32_32x32x16_bf16 v[34:49], v[200:203], v[114:117], v[34:49]
	v_exp_f32_e32 v138, v138
	v_mfma_f32_32x32x16_bf16 v[34:49], v[208:211], v[118:121], v[34:49]
	v_exp_f32_e32 v139, v139
	s_waitcnt lgkmcnt(0)
	v_mfma_f32_32x32x16_bf16 v[18:33], v[196:199], v[82:85], v[18:33]
	v_exp_f32_e32 v140, v140
	v_mfma_f32_32x32x16_bf16 v[18:33], v[204:207], v[86:89], v[18:33]
	v_exp_f32_e32 v141, v141
	ds_read_b64_tr_b16 v[82:83], v0 offset:0x600
	ds_read_b64_tr_b16 v[84:85], v0 offset:0xe00
	ds_read_b64_tr_b16 v[86:87], v0 offset:0x1600
	ds_read_b64_tr_b16 v[88:89], v0 offset:0x1e00
	ds_read_b64_tr_b16 v[114:115], v0 offset:0x2600
	ds_read_b64_tr_b16 v[116:117], v0 offset:0x2e00
	ds_read_b64_tr_b16 v[118:119], v0 offset:0x3600
	ds_read_b64_tr_b16 v[120:121], v0 offset:0x3e00
	v_mfma_f32_32x32x16_bf16 v[18:33], v[200:203], v[90:93], v[18:33]
	v_exp_f32_e32 v142, v142
	v_mfma_f32_32x32x16_bf16 v[18:33], v[208:211], v[94:97], v[18:33]
	v_exp_f32_e32 v143, v143
	s_waitcnt lgkmcnt(0)
	v_mfma_f32_32x32x16_bf16 v[2:17], v[196:199], v[82:85], v[2:17]
	v_exp_f32_e32 v144, v144
	v_mfma_f32_32x32x16_bf16 v[2:17], v[204:207], v[86:89], v[2:17]
	v_exp_f32_e32 v145, v145
	v_mfma_f32_32x32x16_bf16 v[2:17], v[200:203], v[114:117], v[2:17]
	v_exp_f32_e32 v146, v146
	v_mfma_f32_32x32x16_bf16 v[2:17], v[208:211], v[118:121], v[2:17]
	v_exp_f32_e32 v147, v147
	v_cmp_gt_f32_e32 vcc, 1.0, v130
	s_cbranch_vccz .LBB0_461
	s_and_saveexec_b64 s[36:37], s[6:7]
	ds_write_b32 v220, v130 offset:128
	s_or_b64 exec, exec, s[36:37]
	s_waitcnt lgkmcnt(0)
	v_add_u32_e32 v94, v213, v212
	ds_read_b128 v[82:85], v94 offset:224
	ds_read_b128 v[86:89], v94 offset:192
	ds_read_b128 v[90:93], v94 offset:160
	ds_read_b128 v[94:97], v94 offset:128
	s_waitcnt lgkmcnt(3)
	v_pk_mul_f32 v[62:63], v[62:63], v[82:83]
	s_waitcnt lgkmcnt(2)
	v_pk_mul_f32 v[58:59], v[58:59], v[86:87]
	s_waitcnt lgkmcnt(1)
	v_pk_mul_f32 v[54:55], v[54:55], v[90:91]
	v_pk_mul_f32 v[64:65], v[64:65], v[84:85]
	v_pk_mul_f32 v[60:61], v[60:61], v[88:89]
	v_pk_mul_f32 v[56:57], v[56:57], v[92:93]
	s_waitcnt lgkmcnt(0)
	v_pk_mul_f32 v[52:53], v[52:53], v[96:97]
	v_pk_mul_f32 v[50:51], v[50:51], v[94:95]
	v_pk_mul_f32 v[46:47], v[46:47], v[82:83]
	v_pk_mul_f32 v[42:43], v[42:43], v[86:87]
	v_pk_mul_f32 v[38:39], v[38:39], v[90:91]
	v_pk_mul_f32 v[48:49], v[48:49], v[84:85]
	v_pk_mul_f32 v[44:45], v[44:45], v[88:89]
	v_pk_mul_f32 v[40:41], v[40:41], v[92:93]
	v_pk_mul_f32 v[36:37], v[36:37], v[96:97]
	v_pk_mul_f32 v[34:35], v[34:35], v[94:95]
	v_pk_mul_f32 v[30:31], v[30:31], v[82:83]
	v_pk_mul_f32 v[26:27], v[26:27], v[86:87]
	v_pk_mul_f32 v[22:23], v[22:23], v[90:91]
	v_pk_mul_f32 v[32:33], v[32:33], v[84:85]
	v_pk_mul_f32 v[28:29], v[28:29], v[88:89]
	v_pk_mul_f32 v[24:25], v[24:25], v[92:93]
	v_pk_mul_f32 v[20:21], v[20:21], v[96:97]
	v_pk_mul_f32 v[18:19], v[18:19], v[94:95]
	v_pk_mul_f32 v[14:15], v[14:15], v[82:83]
	v_pk_mul_f32 v[10:11], v[10:11], v[86:87]
	v_pk_mul_f32 v[6:7], v[6:7], v[90:91]
	v_pk_mul_f32 v[16:17], v[16:17], v[84:85]
	v_pk_mul_f32 v[12:13], v[12:13], v[88:89]
	v_pk_mul_f32 v[8:9], v[8:9], v[92:93]
	v_pk_mul_f32 v[4:5], v[4:5], v[96:97]
	v_pk_mul_f32 v[2:3], v[2:3], v[94:95]

; #define SBAR() __builtin_amdgcn_sched_barrier(0)
; #define PVE_M(OD, PA, L, H, IDX) do { OD = __builtin_amdgcn_mfma_f32_32x32x16_bf16(PA, PKV(L, H), OD, 0, 0, 0); SBAR(); p[IDX] = __builtin_amdgcn_exp2f(p[IDX]); asm volatile("" : "+v"(p)); SBAR(); } while (0)
; __device__ __forceinline__ void pv_exp(f32x16* o, int vb, bf16x8 pa0, bf16x8 pa1, bf16x8 pa2, bf16x8 pa3, f32x16& p, VF8& fa) {
;   VF8 fb;
;   asm volatile("s_waitcnt lgkmcnt(0)" ::: "memory"); SBAR();
;   PVE_M(o[0], pa0, fa.l0, fa.h0, 0); PVE_M(o[0], pa1, fa.l1, fa.h1, 1); vf8_read<1>(fb, vb); SBAR(); PVE_M(o[0], pa2, fa.l2, fa.h2, 2); PVE_M(o[0], pa3, fa.l3, fa.h3, 3);
;   asm volatile("s_waitcnt lgkmcnt(0)" ::: "memory"); SBAR();
;   PVE_M(o[1], pa0, fb.l0, fb.h0, 4); PVE_M(o[1], pa1, fb.l1, fb.h1, 5); vf8_read<2>(fa, vb); SBAR(); PVE_M(o[1], pa2, fb.l2, fb.h2, 6); PVE_M(o[1], pa3, fb.l3, fb.h3, 7);
;   asm volatile("s_waitcnt lgkmcnt(0)" ::: "memory"); SBAR();
;   PVE_M(o[2], pa0, fa.l0, fa.h0, 8); PVE_M(o[2], pa1, fa.l1, fa.h1, 9); vf8_read<3>(fb, vb); SBAR(); PVE_M(o[2], pa2, fa.l2, fa.h2, 10); PVE_M(o[2], pa3, fa.l3, fa.h3, 11);
;   asm volatile("s_waitcnt lgkmcnt(0)" ::: "memory"); SBAR();
;   PVE_M(o[3], pa0, fb.l0, fb.h0, 12); PVE_M(o[3], pa1, fb.l1, fb.h1, 13); PVE_M(o[3], pa2, fb.l2, fb.h2, 14); PVE_M(o[3], pa3, fb.l3, fb.h3, 15);
; }
.LBB0_463:
	s_waitcnt vmcnt(0)
	s_barrier
	s_add_i32 s79, s97, s100
	s_add_i32 m0, s79, 0x4000
	s_add_i32 s79, s79, 0x6000
	global_load_lds_dwordx4 v[180:181], off
	s_mov_b32 m0, s79
	s_add_i32 s79, s97, s101
	global_load_lds_dwordx4 v[182:183], off
	s_mov_b32 m0, s79
	s_add_i32 s79, s79, 0x380
	global_load_lds_dwordx4 v[214:215], off
	s_mov_b32 m0, s79
	s_nop 0
	global_load_lds_dwordx4 v[214:215], off offset:128
	v_lshl_add_u64 v[180:181], v[180:181], 0, s[76:77]
	v_lshl_add_u64 v[182:183], v[182:183], 0, s[76:77]
	v_lshl_add_u64 v[214:215], v[214:215], 0, s[76:77]
	s_waitcnt lgkmcnt(0)
	v_mfma_f32_32x32x16_bf16 v[50:65], v[132:135], v[144:147], v[50:65]
	v_exp_f32_e32 v114, v114
	v_mfma_f32_32x32x16_bf16 v[50:65], v[136:139], v[106:109], v[50:65]
	v_exp_f32_e32 v115, v115
	ds_read_b64_tr_b16 v[106:107], v203 offset:0x200
	ds_read_b64_tr_b16 v[108:109], v203 offset:0xa00
	ds_read_b64_tr_b16 v[144:145], v203 offset:0x1200
	ds_read_b64_tr_b16 v[146:147], v203 offset:0x1a00
	ds_read_b64_tr_b16 v[204:205], v203 offset:0x2200
	ds_read_b64_tr_b16 v[206:207], v203 offset:0x2a00
	ds_read_b64_tr_b16 v[208:209], v203 offset:0x3200
	ds_read_b64_tr_b16 v[210:211], v203 offset:0x3a00
	v_mfma_f32_32x32x16_bf16 v[50:65], v[196:199], v[102:105], v[50:65]
	v_exp_f32_e32 v116, v116
	v_mfma_f32_32x32x16_bf16 v[50:65], v[140:143], v[98:101], v[50:65]
	v_exp_f32_e32 v117, v117
	s_waitcnt lgkmcnt(0)
	v_mfma_f32_32x32x16_bf16 v[34:49], v[132:135], v[106:109], v[34:49]
	v_exp_f32_e32 v118, v118
	v_mfma_f32_32x32x16_bf16 v[34:49], v[136:139], v[144:147], v[34:49]
	v_exp_f32_e32 v119, v119
	ds_read_b64_tr_b16 v[98:99], v203 offset:0x400
	ds_read_b64_tr_b16 v[100:101], v203 offset:0xc00
	ds_read_b64_tr_b16 v[102:103], v203 offset:0x1400
	ds_read_b64_tr_b16 v[104:105], v203 offset:0x1c00
	ds_read_b64_tr_b16 v[106:107], v203 offset:0x2400
	ds_read_b64_tr_b16 v[108:109], v203 offset:0x2c00
	ds_read_b64_tr_b16 v[144:145], v203 offset:0x3400
	ds_read_b64_tr_b16 v[146:147], v203 offset:0x3c00
	v_mfma_f32_32x32x16_bf16 v[34:49], v[196:199], v[204:207], v[34:49]
	v_exp_f32_e32 v120, v120
	v_mfma_f32_32x32x16_bf16 v[34:49], v[140:143], v[208:211], v[34:49]
	v_exp_f32_e32 v121, v121
	s_waitcnt lgkmcnt(0)
	v_mfma_f32_32x32x16_bf16 v[18:33], v[132:135], v[98:101], v[18:33]
	v_exp_f32_e32 v122, v122
	v_mfma_f32_32x32x16_bf16 v[18:33], v[136:139], v[102:105], v[18:33]
	v_exp_f32_e32 v123, v123
	ds_read_b64_tr_b16 v[98:99], v203 offset:0x600
	ds_read_b64_tr_b16 v[100:101], v203 offset:0xe00
	ds_read_b64_tr_b16 v[102:103], v203 offset:0x1600
	ds_read_b64_tr_b16 v[104:105], v203 offset:0x1e00
	ds_read_b64_tr_b16 v[204:205], v203 offset:0x2600
	ds_read_b64_tr_b16 v[206:207], v203 offset:0x2e00
	ds_read_b64_tr_b16 v[208:209], v203 offset:0x3600
	ds_read_b64_tr_b16 v[210:211], v203 offset:0x3e00
	v_mfma_f32_32x32x16_bf16 v[18:33], v[196:199], v[106:109], v[18:33]
	v_exp_f32_e32 v124, v124
	v_mfma_f32_32x32x16_bf16 v[18:33], v[140:143], v[144:147], v[18:33]
	v_exp_f32_e32 v125, v125
	s_waitcnt lgkmcnt(0)
	v_mfma_f32_32x32x16_bf16 v[2:17], v[132:135], v[98:101], v[2:17]
	v_exp_f32_e32 v126, v126
	v_mfma_f32_32x32x16_bf16 v[2:17], v[136:139], v[102:105], v[2:17]
	v_exp_f32_e32 v127, v127
	v_mfma_f32_32x32x16_bf16 v[2:17], v[196:199], v[204:207], v[2:17]
	v_exp_f32_e32 v128, v128
	v_mfma_f32_32x32x16_bf16 v[2:17], v[140:143], v[208:211], v[2:17]
	v_exp_f32_e32 v129, v129
	v_cmp_gt_f32_e32 vcc, 1.0, v200
	s_cbranch_vccz .LBB0_467
	s_and_saveexec_b64 s[36:37], s[6:7]
	ds_write_b32 v220, v200 offset:128
	s_or_b64 exec, exec, s[36:37]
	s_waitcnt lgkmcnt(0)
	v_add_u32_e32 v110, v213, v212
	ds_read_b128 v[98:101], v110 offset:224
	ds_read_b128 v[102:105], v110 offset:192
	ds_read_b128 v[106:109], v110 offset:160
	ds_read_b128 v[132:135], v110 offset:128
	s_waitcnt lgkmcnt(3)
	v_pk_mul_f32 v[62:63], v[62:63], v[98:99]
	s_waitcnt lgkmcnt(2)
	v_pk_mul_f32 v[58:59], v[58:59], v[102:103]
	s_waitcnt lgkmcnt(1)
	v_pk_mul_f32 v[54:55], v[54:55], v[106:107]
	v_pk_mul_f32 v[64:65], v[64:65], v[100:101]
	v_pk_mul_f32 v[60:61], v[60:61], v[104:105]
	v_pk_mul_f32 v[56:57], v[56:57], v[108:109]
	s_waitcnt lgkmcnt(0)
	v_pk_mul_f32 v[52:53], v[52:53], v[134:135]
	v_pk_mul_f32 v[50:51], v[50:51], v[132:133]
	v_pk_mul_f32 v[46:47], v[46:47], v[98:99]
	v_pk_mul_f32 v[42:43], v[42:43], v[102:103]
	v_pk_mul_f32 v[38:39], v[38:39], v[106:107]
	v_pk_mul_f32 v[48:49], v[48:49], v[100:101]
	v_pk_mul_f32 v[44:45], v[44:45], v[104:105]
	v_pk_mul_f32 v[40:41], v[40:41], v[108:109]
	v_pk_mul_f32 v[36:37], v[36:37], v[134:135]
	v_pk_mul_f32 v[34:35], v[34:35], v[132:133]
	v_pk_mul_f32 v[30:31], v[30:31], v[98:99]
	v_pk_mul_f32 v[26:27], v[26:27], v[102:103]
	v_pk_mul_f32 v[22:23], v[22:23], v[106:107]
	v_pk_mul_f32 v[32:33], v[32:33], v[100:101]
	v_pk_mul_f32 v[28:29], v[28:29], v[104:105]
	v_pk_mul_f32 v[24:25], v[24:25], v[108:109]
	v_pk_mul_f32 v[20:21], v[20:21], v[134:135]
	v_pk_mul_f32 v[18:19], v[18:19], v[132:133]
	v_pk_mul_f32 v[14:15], v[14:15], v[98:99]
	v_pk_mul_f32 v[10:11], v[10:11], v[102:103]
	v_pk_mul_f32 v[6:7], v[6:7], v[106:107]
	v_pk_mul_f32 v[16:17], v[16:17], v[100:101]
	v_pk_mul_f32 v[12:13], v[12:13], v[104:105]
	v_pk_mul_f32 v[8:9], v[8:9], v[108:109]
	v_pk_mul_f32 v[4:5], v[4:5], v[134:135]
	v_pk_mul_f32 v[2:3], v[2:3], v[132:133]
.LBB0_467:
	v_add_f32_e32 v98, v246, v131
	v_add_f32_e32 v98, v245, v98
	v_add_f32_e32 v99, v202, v113
	v_fmac_f32_e32 v98, v244, v219
	v_add_f32_e32 v219, v201, v99
	s_add_i32 s78, s78, 2
	v_fmac_f32_e32 v219, v98, v130
	s_cmpk_gt_u32 s78, 0xfc
	s_waitcnt lgkmcnt(0)
	s_cbranch_scc1 .LBB0_470
	s_xor_b32 s96, s96, 0x10000
	v_mov_b32_e32 v244, v200
	s_branch .LBB0_453

; #define SBAR() __builtin_amdgcn_sched_barrier(0)
; __device__ __forceinline__ unsigned cvtpk(float lo, float hi) { unsigned r; asm volatile("v_cvt_pk_bf16_f32 %0, %1, %2" : "=v"(r) : "v"(lo), "v"(hi)); return r; }
; __device__ __forceinline__ void qkt_fin(f32x16& n0, f32x16& n1, const bf16_t* Ks, const bf16x8* qr, const f32x16& negm, int r32, int hi, ...
;   float psa = 0.f, psb = 0.f; u32x4 wa, wb, wc, wd;
;     ...
; #pragma unroll
;   for (int d0 = 0; d0 < 8; ++d0) { int cb = (d0 * 16 + hi * 8) * 2;
;     bf16x8 b0 = *reinterpret_cast<const bf16x8*>((const char*)Ks + KSWZ(r32, cb));
;     bf16x8 b1 = *reinterpret_cast<const bf16x8*>((const char*)Ks + KSWZ(32 + r32, cb));
;     SBAR(); if (d0 == 0) n0 = __builtin_amdgcn_mfma_f32_32x32x16_bf16(b0, qr[0], negm, 0, 0, 0); else n0 = __builtin_amdgcn_mfma_f32_32x32x16_bf16(b0, qr[d0], n0, 0, 0, 0);
;     SBAR(); QF_CHUNK(2 * d0); SBAR();
;     if (d0 == 0) n1 = __builtin_amdgcn_mfma_f32_32x32x16_bf16(b1, qr[0], negm, 0, 0, 0); else n1 = __builtin_amdgcn_mfma_f32_32x32x16_bf16(b1, qr[d0], n1, 0, 0, 0);
;     SBAR(); QF_CHUNK(2 * d0 + 1); SBAR();
;     if (d0 == 7) { vf8_read<0>(vf0, vbv); SBAR(); } }
;     ...
;   psb += P1[15]; wd[3] = cvtpk(P1[14], P1[15]);
;   l_reg = l_reg * alpha + (psa + psb);
;   pa0 = *reinterpret_cast<bf16x8*>(&wa); pa1 = *reinterpret_cast<bf16x8*>(&wb); pa2 = *reinterpret_cast<bf16x8*>(&wc); pa3 = *reinterpret_cast<bf16x8*>(&wd);
; }
.Lh2_pro:
	v_add_co_u32_e32 v180, vcc, 0xfff7e000, v180
	s_nop 1
	v_addc_co_u32_e32 v181, vcc, -1, v181, vcc
	v_add_co_u32_e32 v182, vcc, 0xfff7e000, v182
	s_nop 1
	v_addc_co_u32_e32 v183, vcc, -1, v183, vcc
	v_add_co_u32_e32 v214, vcc, 0xfff7e000, v214
	s_nop 1
	v_addc_co_u32_e32 v215, vcc, -1, v215, vcc
	s_barrier
.Lh2_453:
	s_add_i32 s97, s96, 0xffff8000
	s_xor_b32 s98, s96, 0x10000
	s_add_i32 s99, s96, 0x8000
	s_and_b32 s99, s99, 0x18000
	s_add_i32 s79, s99, s100
	s_add_i32 m0, s79, 0x4000
	s_add_i32 s79, s79, 0x6000
	global_load_lds_dwordx4 v[180:181], off
	s_mov_b32 m0, s79
	s_add_i32 s79, s99, s101
	global_load_lds_dwordx4 v[182:183], off
	s_mov_b32 m0, s79
	s_add_i32 s79, s79, 0x380
	global_load_lds_dwordx4 v[214:215], off
	s_mov_b32 m0, s79
	s_nop 0
	global_load_lds_dwordx4 v[214:215], off offset:128
	v_lshl_add_u64 v[180:181], v[180:181], 0, s[76:77]
	v_lshl_add_u64 v[182:183], v[182:183], 0, s[76:77]
	v_lshl_add_u64 v[214:215], v[214:215], 0, s[76:77]
	v_add_u32_e32 v196, s96, v236
	ds_read_b128 v[98:101], v196 offset:16384
	ds_read_b128 v[196:199], v196 offset:24576
	v_add_u32_e32 v252, s96, v237
	ds_read_b128 v[248:251], v252 offset:16384
	ds_read_b128 v[252:255], v252 offset:24576
	v_add_u32_e32 v0, s97, v235
	s_waitcnt lgkmcnt(3)
	v_mfma_f32_32x32x16_bf16 v[132:147], v[98:101], v[152:155], v[66:81]
	v_exp_f32_e32 v82, v82
	s_waitcnt lgkmcnt(2)
	v_mfma_f32_32x32x16_bf16 v[98:113], v[196:199], v[152:155], v[66:81]
	v_exp_f32_e32 v83, v83
	v_add_f32_e32 v245, v115, v114
	v_cvt_pk_bf16_f32 v196, v114, v115
	v_add_u32_e32 v206, s96, v238
	ds_read_b128 v[202:205], v206 offset:16384
	ds_read_b128 v[206:209], v206 offset:24576
	s_waitcnt lgkmcnt(3)
	v_mfma_f32_32x32x16_bf16 v[132:147], v[248:251], v[160:163], v[132:147]
	v_exp_f32_e32 v84, v84
	v_add_f32_e32 v245, v116, v245
	v_add_f32_e32 v246, v82, v83
	s_waitcnt lgkmcnt(2)
	v_mfma_f32_32x32x16_bf16 v[98:113], v[252:255], v[160:163], v[98:113]
	v_exp_f32_e32 v85, v85
	v_add_f32_e32 v245, v117, v245
	v_add_f32_e32 v246, v246, v84
	v_cvt_pk_bf16_f32 v197, v116, v117
	v_cvt_pk_bf16_f32 v200, v82, v83
	v_add_u32_e32 v252, s96, v239
	ds_read_b128 v[248:251], v252 offset:16384
	ds_read_b128 v[252:255], v252 offset:24576
	s_waitcnt lgkmcnt(3)
	v_mfma_f32_32x32x16_bf16 v[132:147], v[202:205], v[148:151], v[132:147]
	v_exp_f32_e32 v86, v86
	v_add_f32_e32 v245, v118, v245
	v_add_f32_e32 v246, v246, v85
	s_waitcnt lgkmcnt(2)
	v_mfma_f32_32x32x16_bf16 v[98:113], v[206:209], v[148:151], v[98:113]
	v_exp_f32_e32 v87, v87
	v_add_f32_e32 v245, v119, v245
	v_add_f32_e32 v246, v246, v86
	v_cvt_pk_bf16_f32 v198, v118, v119
	v_cvt_pk_bf16_f32 v201, v84, v85
	v_add_u32_e32 v208, s96, v240
	ds_read_b128 v[204:207], v208 offset:16384
	ds_read_b128 v[208:211], v208 offset:24576
	s_waitcnt lgkmcnt(3)
	v_mfma_f32_32x32x16_bf16 v[132:147], v[248:251], v[156:159], v[132:147]
	v_exp_f32_e32 v88, v88
	v_add_f32_e32 v245, v120, v245
	v_add_f32_e32 v246, v246, v87
	s_waitcnt lgkmcnt(2)
	v_mfma_f32_32x32x16_bf16 v[98:113], v[252:255], v[156:159], v[98:113]
	v_exp_f32_e32 v89, v89
	v_add_f32_e32 v245, v121, v245
	v_add_f32_e32 v246, v246, v88
	v_cvt_pk_bf16_f32 v199, v120, v121
	v_cvt_pk_bf16_f32 v202, v86, v87
	v_add_u32_e32 v252, s96, v241
	ds_read_b128 v[248:251], v252 offset:16384
	ds_read_b128 v[252:255], v252 offset:24576
	s_waitcnt lgkmcnt(3)
	v_mfma_f32_32x32x16_bf16 v[132:147], v[204:207], v[168:171], v[132:147]
	v_exp_f32_e32 v90, v90
	v_add_f32_e32 v245, v122, v245
	v_add_f32_e32 v246, v246, v89
	s_waitcnt lgkmcnt(2)
	v_mfma_f32_32x32x16_bf16 v[98:113], v[208:211], v[168:171], v[98:113]
	v_exp_f32_e32 v91, v91
	v_add_f32_e32 v245, v123, v245
	v_add_f32_e32 v246, v246, v90
	v_cvt_pk_bf16_f32 v204, v122, v123
	v_cvt_pk_bf16_f32 v203, v88, v89
	v_add_u32_e32 v118, s96, v242
	ds_read_b128 v[114:117], v118 offset:16384
	ds_read_b128 v[118:121], v118 offset:24576
	s_waitcnt lgkmcnt(3)
	v_mfma_f32_32x32x16_bf16 v[132:147], v[248:251], v[176:179], v[132:147]
	v_exp_f32_e32 v92, v92
	v_add_f32_e32 v245, v124, v245
	v_add_f32_e32 v246, v246, v91
	s_waitcnt lgkmcnt(2)
	v_mfma_f32_32x32x16_bf16 v[98:113], v[252:255], v[176:179], v[98:113]
	v_exp_f32_e32 v93, v93
	v_add_f32_e32 v245, v125, v245
	v_add_f32_e32 v246, v246, v92
	v_cvt_pk_bf16_f32 v205, v124, v125
	v_cvt_pk_bf16_f32 v208, v90, v91
	v_add_u32_e32 v252, s96, v243
	ds_read_b128 v[248:251], v252 offset:16384
	ds_read_b128 v[252:255], v252 offset:24576
	s_waitcnt lgkmcnt(3)
	v_mfma_f32_32x32x16_bf16 v[132:147], v[114:117], v[164:167], v[132:147]
	v_exp_f32_e32 v94, v94
	v_add_f32_e32 v245, v126, v245
	v_add_f32_e32 v246, v246, v93
	s_waitcnt lgkmcnt(2)
	v_mfma_f32_32x32x16_bf16 v[98:113], v[118:121], v[164:167], v[98:113]
	v_exp_f32_e32 v95, v95
	v_add_f32_e32 v245, v127, v245
	v_add_f32_e32 v246, v246, v94
	v_cvt_pk_bf16_f32 v206, v126, v127
	v_cvt_pk_bf16_f32 v209, v92, v93
	s_waitcnt lgkmcnt(1)
	v_mfma_f32_32x32x16_bf16 v[132:147], v[248:251], v[172:175], v[132:147]
	v_exp_f32_e32 v96, v96
	v_add_f32_e32 v245, v128, v245
	v_add_f32_e32 v246, v246, v95
	s_waitcnt lgkmcnt(0)
	v_mfma_f32_32x32x16_bf16 v[98:113], v[252:255], v[172:175], v[98:113]
	v_exp_f32_e32 v97, v97
	v_add_f32_e32 v245, v129, v245
	v_add_f32_e32 v246, v246, v96
	v_cvt_pk_bf16_f32 v207, v128, v129
	v_cvt_pk_bf16_f32 v210, v94, v95
	v_mov_b32_e32 v131, v97
	v_cvt_pk_bf16_f32 v211, v96, v97
	ds_read_b64_tr_b16 v[94:95], v0 offset:0
	ds_read_b64_tr_b16 v[96:97], v0 offset:2048
	ds_read_b64_tr_b16 v[90:91], v0 offset:4096
	ds_read_b64_tr_b16 v[92:93], v0 offset:6144
	ds_read_b64_tr_b16 v[86:87], v0 offset:8192
	ds_read_b64_tr_b16 v[88:89], v0 offset:10240
	ds_read_b64_tr_b16 v[82:83], v0 offset:12288
	ds_read_b64_tr_b16 v[84:85], v0 offset:14336
	v_cndmask_b32_e64 v114, 0, 1, s[0:1]
	v_cmp_ne_u32_e64 s[8:9], 1, v114
	s_andn2_b64 vcc, exec, s[0:1]
	s_cbranch_vccnz .Lh2_456
; template <bool FIRST, bool DOEXP = true>
; __device__ __forceinline__ void partialSM(f32x16& p0, f32x16& p1, float& m_reg, f32x16& negm, float& alpha, const bool track = true) {
;     ...
;   float pmax = p0[0];
; #pragma unroll
;   for (int r = 1; r < 16; ++r) pmax = fmaxf(pmax, p0[r]);
; #pragma unroll
;   for (int r = 0; r < 16; ++r) pmax = fmaxf(pmax, p1[r]);
;   { auto rr = __builtin_amdgcn_permlane32_swap(__float_as_uint(pmax), __float_as_uint(pmax), false, false);
;     pmax = fmaxf(__uint_as_float(rr[0]), __uint_as_float(rr[1])); }
;   if (!FIRST && __builtin_expect(__all(pmax <= THRL), 1)) { alpha = 1.f; }
;   else { const float dl = FIRST ? pmax : fmaxf(pmax, 0.f); m_reg += dl; alpha = FIRST ? 1.f : __builtin_amdgcn_exp2f(-dl);
; #pragma unroll
;     for (int r = 0; r < 16; ++r) { p0[r] -= dl; p1[r] -= dl; }
; #pragma unroll
;     for (int r = 0; r < 16; ++r) negm[r] = -m_reg;
;     asm volatile("" : "+v"(negm)); }
	v_max_f32_e32 v114, v133, v133
	v_max_f32_e32 v115, v132, v132
	v_max_f32_e32 v114, v115, v114
	v_max3_f32 v114, v114, v134, v135
	v_max3_f32 v114, v114, v136, v137
	v_max3_f32 v114, v114, v138, v139
	v_max3_f32 v114, v114, v140, v141
	v_max3_f32 v114, v114, v142, v143
	v_max3_f32 v114, v114, v144, v145
	v_max3_f32 v114, v114, v146, v147
	v_max3_f32 v114, v114, v98, v99
	v_max3_f32 v114, v114, v100, v101
	v_max3_f32 v114, v114, v102, v103
	v_max3_f32 v114, v114, v104, v105
	v_max3_f32 v114, v114, v106, v107
	v_max3_f32 v114, v114, v108, v109
	v_max3_f32 v114, v114, v110, v111
	v_max3_f32 v114, v114, v112, v113
	v_mov_b32_e32 v115, v114
	s_nop 1
	v_permlane32_swap_b32_e32 v114, v115
	v_max_f32_e32 v115, v115, v115
	v_max_f32_e32 v114, v114, v114
	v_max_f32_e32 v114, v114, v115
	v_cmp_ge_f32_e32 vcc, s69, v114
	s_cmp_eq_u64 vcc, exec
	v_mov_b32_e32 v130, 1.0
	s_cbranch_scc1 .Lh2_457
	v_max_f32_e32 v66, v114, v114
	v_max_f32_e32 v66, 0, v66
	v_exp_f32_e64 v130, -v66
	v_add_f32_e32 v222, v222, v66
	v_sub_f32_e32 v147, v147, v66
	v_sub_f32_e32 v146, v146, v66
	v_sub_f32_e32 v145, v145, v66
	v_sub_f32_e32 v144, v144, v66
	v_sub_f32_e32 v143, v143, v66
	v_sub_f32_e32 v142, v142, v66
	v_sub_f32_e32 v141, v141, v66
	v_sub_f32_e32 v140, v140, v66
	v_sub_f32_e32 v139, v139, v66
	v_sub_f32_e32 v138, v138, v66
	v_sub_f32_e32 v137, v137, v66
	v_sub_f32_e32 v136, v136, v66
	v_sub_f32_e32 v135, v135, v66
	v_sub_f32_e32 v134, v134, v66
	v_sub_f32_e32 v133, v133, v66
	v_sub_f32_e32 v132, v132, v66
	v_sub_f32_e32 v113, v113, v66
	v_sub_f32_e32 v112, v112, v66
	v_sub_f32_e32 v111, v111, v66
	v_sub_f32_e32 v110, v110, v66
	v_sub_f32_e32 v109, v109, v66
	v_sub_f32_e32 v108, v108, v66
	v_sub_f32_e32 v107, v107, v66
	v_sub_f32_e32 v106, v106, v66
	v_sub_f32_e32 v105, v105, v66
	v_sub_f32_e32 v104, v104, v66
	v_sub_f32_e32 v103, v103, v66
	v_sub_f32_e32 v102, v102, v66
	v_sub_f32_e32 v101, v101, v66
	v_sub_f32_e32 v100, v100, v66
	v_sub_f32_e32 v99, v99, v66
	v_sub_f32_e32 v98, v98, v66
	v_xor_b32_e32 v66, 0x80000000, v222
	v_mov_b32_e32 v67, v66
	v_mov_b32_e32 v68, v66
	v_mov_b32_e32 v69, v66
	v_mov_b32_e32 v70, v66
	v_mov_b32_e32 v71, v66
	v_mov_b32_e32 v72, v66
	v_mov_b32_e32 v73, v66
	v_mov_b32_e32 v74, v66
	v_mov_b32_e32 v75, v66
	v_mov_b32_e32 v76, v66
	v_mov_b32_e32 v77, v66
	v_mov_b32_e32 v78, v66
	v_mov_b32_e32 v79, v66
	v_mov_b32_e32 v80, v66
	v_mov_b32_e32 v81, v66
	s_branch .Lh2_457

; #define SBAR() __builtin_amdgcn_sched_barrier(0)
; #define PVE_M(OD, PA, L, H, IDX) do { OD = __builtin_amdgcn_mfma_f32_32x32x16_bf16(PA, PKV(L, H), OD, 0, 0, 0); SBAR(); p[IDX] = __builtin_amdgcn_exp2f(p[IDX]); asm volatile("" : "+v"(p)); SBAR(); } while (0)
; __device__ __forceinline__ void pv_exp(f32x16* o, int vb, bf16x8 pa0, bf16x8 pa1, bf16x8 pa2, bf16x8 pa3, f32x16& p, VF8& fa) {
;   VF8 fb;
;   asm volatile("s_waitcnt lgkmcnt(0)" ::: "memory"); SBAR();
;   PVE_M(o[0], pa0, fa.l0, fa.h0, 0); PVE_M(o[0], pa1, fa.l1, fa.h1, 1); vf8_read<1>(fb, vb); SBAR(); PVE_M(o[0], pa2, fa.l2, fa.h2, 2); PVE_M(o[0], pa3, fa.l3, fa.h3, 3);
;   asm volatile("s_waitcnt lgkmcnt(0)" ::: "memory"); SBAR();
;   PVE_M(o[1], pa0, fb.l0, fb.h0, 4); PVE_M(o[1], pa1, fb.l1, fb.h1, 5); vf8_read<2>(fa, vb); SBAR(); PVE_M(o[1], pa2, fb.l2, fb.h2, 6); PVE_M(o[1], pa3, fb.l3, fb.h3, 7);
;   asm volatile("s_waitcnt lgkmcnt(0)" ::: "memory"); SBAR();
;   PVE_M(o[2], pa0, fa.l0, fa.h0, 8); PVE_M(o[2], pa1, fa.l1, fa.h1, 9); vf8_read<3>(fb, vb); SBAR(); PVE_M(o[2], pa2, fa.l2, fa.h2, 10); PVE_M(o[2], pa3, fa.l3, fa.h3, 11);
;   asm volatile("s_waitcnt lgkmcnt(0)" ::: "memory"); SBAR();
;   PVE_M(o[3], pa0, fb.l0, fb.h0, 12); PVE_M(o[3], pa1, fb.l1, fb.h1, 13); PVE_M(o[3], pa2, fb.l2, fb.h2, 14); PVE_M(o[3], pa3, fb.l3, fb.h3, 15);
; }
.Lh2_457:
	s_waitcnt lgkmcnt(0)
	v_mfma_f32_32x32x16_bf16 v[50:65], v[196:199], v[94:97], v[50:65]
	v_exp_f32_e32 v132, v132
	v_mfma_f32_32x32x16_bf16 v[50:65], v[204:207], v[90:93], v[50:65]
	v_exp_f32_e32 v133, v133
	ds_read_b64_tr_b16 v[90:91], v0 offset:0x200
	ds_read_b64_tr_b16 v[92:93], v0 offset:0xa00
	ds_read_b64_tr_b16 v[94:95], v0 offset:0x1200
	ds_read_b64_tr_b16 v[96:97], v0 offset:0x1a00
	ds_read_b64_tr_b16 v[114:115], v0 offset:0x2200
	ds_read_b64_tr_b16 v[116:117], v0 offset:0x2a00
	ds_read_b64_tr_b16 v[118:119], v0 offset:0x3200
	ds_read_b64_tr_b16 v[120:121], v0 offset:0x3a00
	v_mfma_f32_32x32x16_bf16 v[50:65], v[200:203], v[86:89], v[50:65]
	v_exp_f32_e32 v134, v134
	v_mfma_f32_32x32x16_bf16 v[50:65], v[208:211], v[82:85], v[50:65]
	v_exp_f32_e32 v135, v135
	s_waitcnt lgkmcnt(0)
	v_mfma_f32_32x32x16_bf16 v[34:49], v[196:199], v[90:93], v[34:49]
	v_exp_f32_e32 v136, v136
	v_mfma_f32_32x32x16_bf16 v[34:49], v[204:207], v[94:97], v[34:49]
	v_exp_f32_e32 v137, v137
	ds_read_b64_tr_b16 v[82:83], v0 offset:0x400
	ds_read_b64_tr_b16 v[84:85], v0 offset:0xc00
	ds_read_b64_tr_b16 v[86:87], v0 offset:0x1400
	ds_read_b64_tr_b16 v[88:89], v0 offset:0x1c00
	ds_read_b64_tr_b16 v[90:91], v0 offset:0x2400
	ds_read_b64_tr_b16 v[92:93], v0 offset:0x2c00
	ds_read_b64_tr_b16 v[94:95], v0 offset:0x3400
	ds_read_b64_tr_b16 v[96:97], v0 offset:0x3c00
	v_mfma_f32_32x32x16_bf16 v[34:49], v[200:203], v[114:117], v[34:49]
	v_exp_f32_e32 v138, v138
	v_mfma_f32_32x32x16_bf16 v[34:49], v[208:211], v[118:121], v[34:49]
	v_exp_f32_e32 v139, v139
	s_waitcnt lgkmcnt(0)
	v_mfma_f32_32x32x16_bf16 v[18:33], v[196:199], v[82:85], v[18:33]
	v_exp_f32_e32 v140, v140
	v_mfma_f32_32x32x16_bf16 v[18:33], v[204:207], v[86:89], v[18:33]
	v_exp_f32_e32 v141, v141
	ds_read_b64_tr_b16 v[82:83], v0 offset:0x600
	ds_read_b64_tr_b16 v[84:85], v0 offset:0xe00
	ds_read_b64_tr_b16 v[86:87], v0 offset:0x1600
	ds_read_b64_tr_b16 v[88:89], v0 offset:0x1e00
	ds_read_b64_tr_b16 v[114:115], v0 offset:0x2600
	ds_read_b64_tr_b16 v[116:117], v0 offset:0x2e00
	ds_read_b64_tr_b16 v[118:119], v0 offset:0x3600
	ds_read_b64_tr_b16 v[120:121], v0 offset:0x3e00
	v_mfma_f32_32x32x16_bf16 v[18:33], v[200:203], v[90:93], v[18:33]
	v_exp_f32_e32 v142, v142
	v_mfma_f32_32x32x16_bf16 v[18:33], v[208:211], v[94:97], v[18:33]
	v_exp_f32_e32 v143, v143
	s_waitcnt lgkmcnt(0)
	v_mfma_f32_32x32x16_bf16 v[2:17], v[196:199], v[82:85], v[2:17]
	v_exp_f32_e32 v144, v144
	v_mfma_f32_32x32x16_bf16 v[2:17], v[204:207], v[86:89], v[2:17]
	v_exp_f32_e32 v145, v145
	v_mfma_f32_32x32x16_bf16 v[2:17], v[200:203], v[114:117], v[2:17]
	v_exp_f32_e32 v146, v146
	v_mfma_f32_32x32x16_bf16 v[2:17], v[208:211], v[118:121], v[2:17]
	v_exp_f32_e32 v147, v147
	v_cmp_gt_f32_e32 vcc, 1.0, v130
	s_cbranch_vccz .Lh2_461
	s_and_saveexec_b64 s[36:37], s[6:7]
	ds_write_b32 v220, v130 offset:128
	s_or_b64 exec, exec, s[36:37]
	s_waitcnt lgkmcnt(0)
	v_add_u32_e32 v94, v213, v212
	ds_read_b128 v[82:85], v94 offset:224
	ds_read_b128 v[86:89], v94 offset:192
	ds_read_b128 v[90:93], v94 offset:160
	ds_read_b128 v[94:97], v94 offset:128
	s_waitcnt lgkmcnt(3)
	v_pk_mul_f32 v[62:63], v[62:63], v[82:83]
	s_waitcnt lgkmcnt(2)
	v_pk_mul_f32 v[58:59], v[58:59], v[86:87]
	s_waitcnt lgkmcnt(1)
	v_pk_mul_f32 v[54:55], v[54:55], v[90:91]
	v_pk_mul_f32 v[64:65], v[64:65], v[84:85]
	v_pk_mul_f32 v[60:61], v[60:61], v[88:89]
	v_pk_mul_f32 v[56:57], v[56:57], v[92:93]
	s_waitcnt lgkmcnt(0)
	v_pk_mul_f32 v[52:53], v[52:53], v[96:97]
	v_pk_mul_f32 v[50:51], v[50:51], v[94:95]
	v_pk_mul_f32 v[46:47], v[46:47], v[82:83]
	v_pk_mul_f32 v[42:43], v[42:43], v[86:87]
	v_pk_mul_f32 v[38:39], v[38:39], v[90:91]
	v_pk_mul_f32 v[48:49], v[48:49], v[84:85]
	v_pk_mul_f32 v[44:45], v[44:45], v[88:89]
	v_pk_mul_f32 v[40:41], v[40:41], v[92:93]
	v_pk_mul_f32 v[36:37], v[36:37], v[96:97]
	v_pk_mul_f32 v[34:35], v[34:35], v[94:95]
	v_pk_mul_f32 v[30:31], v[30:31], v[82:83]
	v_pk_mul_f32 v[26:27], v[26:27], v[86:87]
	v_pk_mul_f32 v[22:23], v[22:23], v[90:91]
	v_pk_mul_f32 v[32:33], v[32:33], v[84:85]
	v_pk_mul_f32 v[28:29], v[28:29], v[88:89]
	v_pk_mul_f32 v[24:25], v[24:25], v[92:93]
	v_pk_mul_f32 v[20:21], v[20:21], v[96:97]
	v_pk_mul_f32 v[18:19], v[18:19], v[94:95]
	v_pk_mul_f32 v[14:15], v[14:15], v[82:83]
	v_pk_mul_f32 v[10:11], v[10:11], v[86:87]
	v_pk_mul_f32 v[6:7], v[6:7], v[90:91]
	v_pk_mul_f32 v[16:17], v[16:17], v[84:85]
	v_pk_mul_f32 v[12:13], v[12:13], v[88:89]
	v_pk_mul_f32 v[8:9], v[8:9], v[92:93]
	v_pk_mul_f32 v[4:5], v[4:5], v[96:97]
	v_pk_mul_f32 v[2:3], v[2:3], v[94:95]
; #define SBAR() __builtin_amdgcn_sched_barrier(0)
; __device__ __forceinline__ unsigned cvtpk(float lo, float hi) { unsigned r; asm volatile("v_cvt_pk_bf16_f32 %0, %1, %2" : "=v"(r) : "v"(lo), "v"(hi)); return r; }
; __device__ __forceinline__ void qkt_fin(f32x16& n0, f32x16& n1, const bf16_t* Ks, const bf16x8* qr, const f32x16& negm, int r32, int hi, ...
;   float psa = 0.f, psb = 0.f; u32x4 wa, wb, wc, wd;
;     ...
; #pragma unroll
;   for (int d0 = 0; d0 < 8; ++d0) { int cb = (d0 * 16 + hi * 8) * 2;
;     bf16x8 b0 = *reinterpret_cast<const bf16x8*>((const char*)Ks + KSWZ(r32, cb));
;     bf16x8 b1 = *reinterpret_cast<const bf16x8*>((const char*)Ks + KSWZ(32 + r32, cb));
;     SBAR(); if (d0 == 0) n0 = __builtin_amdgcn_mfma_f32_32x32x16_bf16(b0, qr[0], negm, 0, 0, 0); else n0 = __builtin_amdgcn_mfma_f32_32x32x16_bf16(b0, qr[d0], n0, 0, 0, 0);
;     SBAR(); QF_CHUNK(2 * d0); SBAR();
;     if (d0 == 0) n1 = __builtin_amdgcn_mfma_f32_32x32x16_bf16(b1, qr[0], negm, 0, 0, 0); else n1 = __builtin_amdgcn_mfma_f32_32x32x16_bf16(b1, qr[d0], n1, 0, 0, 0);
;     SBAR(); QF_CHUNK(2 * d0 + 1); SBAR();
;     if (d0 == 7) { vf8_read<0>(vf0, vbv); SBAR(); } }
;     ...
;   psb += P1[15]; wd[3] = cvtpk(P1[14], P1[15]);
;   l_reg = l_reg * alpha + (psa + psb);
;   pa0 = *reinterpret_cast<bf16x8*>(&wa); pa1 = *reinterpret_cast<bf16x8*>(&wb); pa2 = *reinterpret_cast<bf16x8*>(&wc); pa3 = *reinterpret_cast<bf16x8*>(&wd);
; }
.Lh2_461:
	s_waitcnt lgkmcnt(0)
	s_waitcnt vmcnt(0)
	s_barrier
	s_add_i32 s79, s98, s100
	s_add_i32 m0, s79, 0x4000
	s_add_i32 s79, s79, 0x6000
	global_load_lds_dwordx4 v[180:181], off
	s_mov_b32 m0, s79
	s_add_i32 s79, s98, s101
	global_load_lds_dwordx4 v[182:183], off
	s_mov_b32 m0, s79
	s_add_i32 s79, s79, 0x380
	global_load_lds_dwordx4 v[214:215], off
	s_mov_b32 m0, s79
	s_nop 0
	global_load_lds_dwordx4 v[214:215], off offset:128
	v_lshl_add_u64 v[180:181], v[180:181], 0, s[76:77]
	v_lshl_add_u64 v[182:183], v[182:183], 0, s[76:77]
	v_lshl_add_u64 v[214:215], v[214:215], 0, s[76:77]
	v_add_u32_e32 v208, s99, v236
	ds_read_b128 v[204:207], v208 offset:16384
	ds_read_b128 v[208:211], v208 offset:24576
	v_add_u32_e32 v252, s99, v237
	ds_read_b128 v[248:251], v252 offset:16384
	ds_read_b128 v[252:255], v252 offset:24576
	v_add_u32_e32 v203, s96, v235
	s_waitcnt lgkmcnt(3)
	v_mfma_f32_32x32x16_bf16 v[114:129], v[204:207], v[152:155], v[66:81]
	v_exp_f32_e32 v98, v98
	s_waitcnt lgkmcnt(2)
	v_mfma_f32_32x32x16_bf16 v[82:97], v[208:211], v[152:155], v[66:81]
	v_exp_f32_e32 v99, v99
	v_add_f32_e32 v201, v133, v132
	v_cvt_pk_bf16_f32 v132, v132, v133
	v_add_u32_e32 v208, s99, v238
	ds_read_b128 v[204:207], v208 offset:16384
	ds_read_b128 v[208:211], v208 offset:24576
	s_waitcnt lgkmcnt(3)
	v_mfma_f32_32x32x16_bf16 v[114:129], v[248:251], v[160:163], v[114:129]
	v_exp_f32_e32 v100, v100
	v_add_f32_e32 v201, v134, v201
	v_add_f32_e32 v202, v98, v99
	s_waitcnt lgkmcnt(2)
	v_mfma_f32_32x32x16_bf16 v[82:97], v[252:255], v[160:163], v[82:97]
	v_exp_f32_e32 v101, v101
	v_add_f32_e32 v201, v135, v201
	v_add_f32_e32 v202, v202, v100
	v_cvt_pk_bf16_f32 v133, v134, v135
	v_cvt_pk_bf16_f32 v196, v98, v99
	v_add_u32_e32 v252, s99, v239
	ds_read_b128 v[248:251], v252 offset:16384
	ds_read_b128 v[252:255], v252 offset:24576
	s_waitcnt lgkmcnt(3)
	v_mfma_f32_32x32x16_bf16 v[114:129], v[204:207], v[148:151], v[114:129]
	v_exp_f32_e32 v102, v102
	v_add_f32_e32 v201, v136, v201
	v_add_f32_e32 v202, v202, v101
	s_waitcnt lgkmcnt(2)
	v_mfma_f32_32x32x16_bf16 v[82:97], v[208:211], v[148:151], v[82:97]
	v_exp_f32_e32 v103, v103
	v_add_f32_e32 v201, v137, v201
	v_add_f32_e32 v202, v202, v102
	v_cvt_pk_bf16_f32 v134, v136, v137
	v_cvt_pk_bf16_f32 v197, v100, v101
	v_add_u32_e32 v208, s99, v240
	ds_read_b128 v[204:207], v208 offset:16384
	ds_read_b128 v[208:211], v208 offset:24576
	s_waitcnt lgkmcnt(3)
	v_mfma_f32_32x32x16_bf16 v[114:129], v[248:251], v[156:159], v[114:129]
	v_exp_f32_e32 v104, v104
	v_add_f32_e32 v201, v138, v201
	v_add_f32_e32 v202, v202, v103
	s_waitcnt lgkmcnt(2)
	v_mfma_f32_32x32x16_bf16 v[82:97], v[252:255], v[156:159], v[82:97]
	v_exp_f32_e32 v105, v105
	v_add_f32_e32 v201, v139, v201
	v_add_f32_e32 v202, v202, v104
	v_cvt_pk_bf16_f32 v135, v138, v139
	v_cvt_pk_bf16_f32 v198, v102, v103
	v_add_u32_e32 v252, s99, v241
	ds_read_b128 v[248:251], v252 offset:16384
	ds_read_b128 v[252:255], v252 offset:24576
	s_waitcnt lgkmcnt(3)
	v_mfma_f32_32x32x16_bf16 v[114:129], v[204:207], v[168:171], v[114:129]
	v_exp_f32_e32 v106, v106
	v_add_f32_e32 v201, v140, v201
	v_add_f32_e32 v202, v202, v105
	s_waitcnt lgkmcnt(2)
	v_mfma_f32_32x32x16_bf16 v[82:97], v[208:211], v[168:171], v[82:97]
	v_exp_f32_e32 v107, v107
	v_add_f32_e32 v201, v141, v201
	v_add_f32_e32 v202, v202, v106
	v_cvt_pk_bf16_f32 v136, v140, v141
	v_cvt_pk_bf16_f32 v199, v104, v105
	v_add_u32_e32 v208, s99, v242
	ds_read_b128 v[204:207], v208 offset:16384
	ds_read_b128 v[208:211], v208 offset:24576
	s_waitcnt lgkmcnt(3)
	v_mfma_f32_32x32x16_bf16 v[114:129], v[248:251], v[176:179], v[114:129]
	v_exp_f32_e32 v108, v108
	v_add_f32_e32 v201, v142, v201
	v_add_f32_e32 v202, v202, v107
	s_waitcnt lgkmcnt(2)
	v_mfma_f32_32x32x16_bf16 v[82:97], v[252:255], v[176:179], v[82:97]
	v_exp_f32_e32 v109, v109
	v_add_f32_e32 v201, v143, v201
	v_add_f32_e32 v202, v202, v108
	v_cvt_pk_bf16_f32 v137, v142, v143
	v_cvt_pk_bf16_f32 v140, v106, v107
	v_add_u32_e32 v252, s99, v243
	ds_read_b128 v[248:251], v252 offset:16384
	ds_read_b128 v[252:255], v252 offset:24576
	s_waitcnt lgkmcnt(3)
	v_mfma_f32_32x32x16_bf16 v[114:129], v[204:207], v[164:167], v[114:129]
	v_exp_f32_e32 v110, v110
	v_add_f32_e32 v201, v144, v201
	v_add_f32_e32 v202, v202, v109
	s_waitcnt lgkmcnt(2)
	v_mfma_f32_32x32x16_bf16 v[82:97], v[208:211], v[164:167], v[82:97]
	v_exp_f32_e32 v111, v111
	v_add_f32_e32 v201, v145, v201
	v_add_f32_e32 v202, v202, v110
	v_cvt_pk_bf16_f32 v138, v144, v145
	v_cvt_pk_bf16_f32 v141, v108, v109
	s_waitcnt lgkmcnt(1)
	v_mfma_f32_32x32x16_bf16 v[114:129], v[248:251], v[172:175], v[114:129]
	v_exp_f32_e32 v112, v112
	v_add_f32_e32 v201, v146, v201
	v_add_f32_e32 v202, v202, v111
	s_waitcnt lgkmcnt(0)
	v_mfma_f32_32x32x16_bf16 v[82:97], v[252:255], v[172:175], v[82:97]
	v_exp_f32_e32 v113, v113
	v_add_f32_e32 v201, v147, v201
	v_add_f32_e32 v202, v202, v112
	v_cvt_pk_bf16_f32 v139, v146, v147
	v_cvt_pk_bf16_f32 v142, v110, v111
	ds_read_b64_tr_b16 v[144:145], v203 offset:0
	ds_read_b64_tr_b16 v[146:147], v203 offset:2048
	s_nop 0
	ds_read_b64_tr_b16 v[106:107], v203 offset:4096
	ds_read_b64_tr_b16 v[108:109], v203 offset:6144
	ds_read_b64_tr_b16 v[102:103], v203 offset:8192
	ds_read_b64_tr_b16 v[104:105], v203 offset:10240
	ds_read_b64_tr_b16 v[98:99], v203 offset:12288
	ds_read_b64_tr_b16 v[100:101], v203 offset:14336
	v_cvt_pk_bf16_f32 v143, v112, v113
	s_and_b64 vcc, exec, s[8:9]
	v_mov_b32_e32 v200, 1.0
	s_cbranch_vccnz .Lh2_463
	v_max_f32_e32 v110, v115, v115
	v_max_f32_e32 v111, v114, v114
	v_max_f32_e32 v110, v111, v110
	v_max3_f32 v110, v110, v116, v117
	v_max3_f32 v110, v110, v118, v119
	v_max3_f32 v110, v110, v120, v121
	v_max3_f32 v110, v110, v122, v123
	v_max3_f32 v110, v110, v124, v125
	v_max3_f32 v110, v110, v126, v127
	v_max3_f32 v110, v110, v128, v129
	v_max3_f32 v110, v110, v82, v83
	v_max3_f32 v110, v110, v84, v85
	v_max3_f32 v110, v110, v86, v87
	v_max3_f32 v110, v110, v88, v89
	v_max3_f32 v110, v110, v90, v91
	v_max3_f32 v110, v110, v92, v93
	v_max3_f32 v110, v110, v94, v95
	v_max3_f32 v110, v110, v96, v97
	v_mov_b32_e32 v111, v110
	s_nop 1
	v_permlane32_swap_b32_e32 v110, v111
	v_max_f32_e32 v111, v111, v111
	v_max_f32_e32 v110, v110, v110
	v_max_f32_e32 v110, v110, v111
	v_cmp_ge_f32_e32 vcc, s69, v110
	s_cmp_eq_u64 vcc, exec
	v_mov_b32_e32 v200, 1.0
	s_cbranch_scc0 .Lh2_469
; #define SBAR() __builtin_amdgcn_sched_barrier(0)
; #define PVE_M(OD, PA, L, H, IDX) do { OD = __builtin_amdgcn_mfma_f32_32x32x16_bf16(PA, PKV(L, H), OD, 0, 0, 0); SBAR(); p[IDX] = __builtin_amdgcn_exp2f(p[IDX]); asm volatile("" : "+v"(p)); SBAR(); } while (0)
; __device__ __forceinline__ void pv_exp(f32x16* o, int vb, bf16x8 pa0, bf16x8 pa1, bf16x8 pa2, bf16x8 pa3, f32x16& p, VF8& fa) {
;   VF8 fb;
;   asm volatile("s_waitcnt lgkmcnt(0)" ::: "memory"); SBAR();
;   PVE_M(o[0], pa0, fa.l0, fa.h0, 0); PVE_M(o[0], pa1, fa.l1, fa.h1, 1); vf8_read<1>(fb, vb); SBAR(); PVE_M(o[0], pa2, fa.l2, fa.h2, 2); PVE_M(o[0], pa3, fa.l3, fa.h3, 3);
;   asm volatile("s_waitcnt lgkmcnt(0)" ::: "memory"); SBAR();
;   PVE_M(o[1], pa0, fb.l0, fb.h0, 4); PVE_M(o[1], pa1, fb.l1, fb.h1, 5); vf8_read<2>(fa, vb); SBAR(); PVE_M(o[1], pa2, fb.l2, fb.h2, 6); PVE_M(o[1], pa3, fb.l3, fb.h3, 7);
;   asm volatile("s_waitcnt lgkmcnt(0)" ::: "memory"); SBAR();
;   PVE_M(o[2], pa0, fa.l0, fa.h0, 8); PVE_M(o[2], pa1, fa.l1, fa.h1, 9); vf8_read<3>(fb, vb); SBAR(); PVE_M(o[2], pa2, fa.l2, fa.h2, 10); PVE_M(o[2], pa3, fa.l3, fa.h3, 11);
;   asm volatile("s_waitcnt lgkmcnt(0)" ::: "memory"); SBAR();
;   PVE_M(o[3], pa0, fb.l0, fb.h0, 12); PVE_M(o[3], pa1, fb.l1, fb.h1, 13); PVE_M(o[3], pa2, fb.l2, fb.h2, 14); PVE_M(o[3], pa3, fb.l3, fb.h3, 15);
; }
.Lh2_463:
	s_waitcnt lgkmcnt(0)
	v_mfma_f32_32x32x16_bf16 v[50:65], v[132:135], v[144:147], v[50:65]
	v_exp_f32_e32 v114, v114
	v_mfma_f32_32x32x16_bf16 v[50:65], v[136:139], v[106:109], v[50:65]
	v_exp_f32_e32 v115, v115
	ds_read_b64_tr_b16 v[106:107], v203 offset:0x200
	ds_read_b64_tr_b16 v[108:109], v203 offset:0xa00
	ds_read_b64_tr_b16 v[144:145], v203 offset:0x1200
	ds_read_b64_tr_b16 v[146:147], v203 offset:0x1a00
	ds_read_b64_tr_b16 v[204:205], v203 offset:0x2200
	ds_read_b64_tr_b16 v[206:207], v203 offset:0x2a00
	ds_read_b64_tr_b16 v[208:209], v203 offset:0x3200
	ds_read_b64_tr_b16 v[210:211], v203 offset:0x3a00
	v_mfma_f32_32x32x16_bf16 v[50:65], v[196:199], v[102:105], v[50:65]
	v_exp_f32_e32 v116, v116
	v_mfma_f32_32x32x16_bf16 v[50:65], v[140:143], v[98:101], v[50:65]
	v_exp_f32_e32 v117, v117
	s_waitcnt lgkmcnt(0)
	v_mfma_f32_32x32x16_bf16 v[34:49], v[132:135], v[106:109], v[34:49]
	v_exp_f32_e32 v118, v118
	v_mfma_f32_32x32x16_bf16 v[34:49], v[136:139], v[144:147], v[34:49]
	v_exp_f32_e32 v119, v119
	ds_read_b64_tr_b16 v[98:99], v203 offset:0x400
	ds_read_b64_tr_b16 v[100:101], v203 offset:0xc00
	ds_read_b64_tr_b16 v[102:103], v203 offset:0x1400
	ds_read_b64_tr_b16 v[104:105], v203 offset:0x1c00
	ds_read_b64_tr_b16 v[106:107], v203 offset:0x2400
	ds_read_b64_tr_b16 v[108:109], v203 offset:0x2c00
	ds_read_b64_tr_b16 v[144:145], v203 offset:0x3400
	ds_read_b64_tr_b16 v[146:147], v203 offset:0x3c00
	v_mfma_f32_32x32x16_bf16 v[34:49], v[196:199], v[204:207], v[34:49]
	v_exp_f32_e32 v120, v120
	v_mfma_f32_32x32x16_bf16 v[34:49], v[140:143], v[208:211], v[34:49]
	v_exp_f32_e32 v121, v121
	s_waitcnt lgkmcnt(0)
	v_mfma_f32_32x32x16_bf16 v[18:33], v[132:135], v[98:101], v[18:33]
	v_exp_f32_e32 v122, v122
	v_mfma_f32_32x32x16_bf16 v[18:33], v[136:139], v[102:105], v[18:33]
	v_exp_f32_e32 v123, v123
	ds_read_b64_tr_b16 v[98:99], v203 offset:0x600
	ds_read_b64_tr_b16 v[100:101], v203 offset:0xe00
	ds_read_b64_tr_b16 v[102:103], v203 offset:0x1600
	ds_read_b64_tr_b16 v[104:105], v203 offset:0x1e00
	ds_read_b64_tr_b16 v[204:205], v203 offset:0x2600
	ds_read_b64_tr_b16 v[206:207], v203 offset:0x2e00
	ds_read_b64_tr_b16 v[208:209], v203 offset:0x3600
	ds_read_b64_tr_b16 v[210:211], v203 offset:0x3e00
	v_mfma_f32_32x32x16_bf16 v[18:33], v[196:199], v[106:109], v[18:33]
	v_exp_f32_e32 v124, v124
	v_mfma_f32_32x32x16_bf16 v[18:33], v[140:143], v[144:147], v[18:33]
	v_exp_f32_e32 v125, v125
	s_waitcnt lgkmcnt(0)
	v_mfma_f32_32x32x16_bf16 v[2:17], v[132:135], v[98:101], v[2:17]
	v_exp_f32_e32 v126, v126
	v_mfma_f32_32x32x16_bf16 v[2:17], v[136:139], v[102:105], v[2:17]
	v_exp_f32_e32 v127, v127
	v_mfma_f32_32x32x16_bf16 v[2:17], v[196:199], v[204:207], v[2:17]
	v_exp_f32_e32 v128, v128
	v_mfma_f32_32x32x16_bf16 v[2:17], v[140:143], v[208:211], v[2:17]
	v_exp_f32_e32 v129, v129
	v_cmp_gt_f32_e32 vcc, 1.0, v200
	s_cbranch_vccz .Lh2_467
	s_and_saveexec_b64 s[36:37], s[6:7]
	ds_write_b32 v220, v200 offset:128
	s_or_b64 exec, exec, s[36:37]
	s_waitcnt lgkmcnt(0)
	v_add_u32_e32 v110, v213, v212
	ds_read_b128 v[98:101], v110 offset:224
	ds_read_b128 v[102:105], v110 offset:192
	ds_read_b128 v[106:109], v110 offset:160
	ds_read_b128 v[132:135], v110 offset:128
	s_waitcnt lgkmcnt(3)
	v_pk_mul_f32 v[62:63], v[62:63], v[98:99]
	s_waitcnt lgkmcnt(2)
	v_pk_mul_f32 v[58:59], v[58:59], v[102:103]
	s_waitcnt lgkmcnt(1)
	v_pk_mul_f32 v[54:55], v[54:55], v[106:107]
	v_pk_mul_f32 v[64:65], v[64:65], v[100:101]
	v_pk_mul_f32 v[60:61], v[60:61], v[104:105]
	v_pk_mul_f32 v[56:57], v[56:57], v[108:109]
	s_waitcnt lgkmcnt(0)
	v_pk_mul_f32 v[52:53], v[52:53], v[134:135]
	v_pk_mul_f32 v[50:51], v[50:51], v[132:133]
	v_pk_mul_f32 v[46:47], v[46:47], v[98:99]
	v_pk_mul_f32 v[42:43], v[42:43], v[102:103]
	v_pk_mul_f32 v[38:39], v[38:39], v[106:107]
	v_pk_mul_f32 v[48:49], v[48:49], v[100:101]
	v_pk_mul_f32 v[44:45], v[44:45], v[104:105]
	v_pk_mul_f32 v[40:41], v[40:41], v[108:109]
	v_pk_mul_f32 v[36:37], v[36:37], v[134:135]
	v_pk_mul_f32 v[34:35], v[34:35], v[132:133]
	v_pk_mul_f32 v[30:31], v[30:31], v[98:99]
	v_pk_mul_f32 v[26:27], v[26:27], v[102:103]
	v_pk_mul_f32 v[22:23], v[22:23], v[106:107]
	v_pk_mul_f32 v[32:33], v[32:33], v[100:101]
	v_pk_mul_f32 v[28:29], v[28:29], v[104:105]
	v_pk_mul_f32 v[24:25], v[24:25], v[108:109]
	v_pk_mul_f32 v[20:21], v[20:21], v[134:135]
	v_pk_mul_f32 v[18:19], v[18:19], v[132:133]
	v_pk_mul_f32 v[14:15], v[14:15], v[98:99]
	v_pk_mul_f32 v[10:11], v[10:11], v[102:103]
	v_pk_mul_f32 v[6:7], v[6:7], v[106:107]
	v_pk_mul_f32 v[16:17], v[16:17], v[100:101]
	v_pk_mul_f32 v[12:13], v[12:13], v[104:105]
	v_pk_mul_f32 v[8:9], v[8:9], v[108:109]
	v_pk_mul_f32 v[4:5], v[4:5], v[134:135]
	v_pk_mul_f32 v[2:3], v[2:3], v[132:133]
.Lh2_467:
	v_add_f32_e32 v98, v246, v131
	v_add_f32_e32 v98, v245, v98
	v_add_f32_e32 v99, v202, v113
	v_fmac_f32_e32 v98, v244, v219
	v_add_f32_e32 v219, v201, v99
	s_add_i32 s78, s78, 2
	v_fmac_f32_e32 v219, v98, v130
	s_cmpk_gt_u32 s78, 0xfc
	s_waitcnt lgkmcnt(0)
	s_waitcnt vmcnt(0)
	s_barrier
	s_cbranch_scc1 .LBB0_470
	s_xor_b32 s96, s96, 0x10000
	v_mov_b32_e32 v244, v200
	s_branch .Lh2_453

; __global__ void __launch_bounds__(512, 2) fwd_megakernel(Args a) {
;   extern __shared__ __attribute__((aligned(16))) unsigned char lds[];
;   cg::grid_group grid = cg::this_grid();
;   const int G = gridDim.x, c = blockIdx.x, wid_s = __builtin_amdgcn_readfirstlane((int)threadIdx.x >> 6);
	.amdhsa_kernel _Z14fwd_megakernel4Args
		.amdhsa_group_segment_fixed_size 0
		.amdhsa_private_segment_fixed_size 0
		.amdhsa_kernarg_size 352
		.amdhsa_user_sgpr_count 2
		.amdhsa_user_sgpr_dispatch_ptr 0
		.amdhsa_user_sgpr_queue_ptr 0
		.amdhsa_user_sgpr_kernarg_segment_ptr 1
		.amdhsa_user_sgpr_dispatch_id 0
		.amdhsa_user_sgpr_kernarg_preload_length 0
		.amdhsa_user_sgpr_kernarg_preload_offset 0
		.amdhsa_user_sgpr_private_segment_size 0
		.amdhsa_uses_dynamic_stack 0
		.amdhsa_enable_private_segment 0
		.amdhsa_system_sgpr_workgroup_id_x 1
		.amdhsa_system_sgpr_workgroup_id_y 0
		.amdhsa_system_sgpr_workgroup_id_z 0
		.amdhsa_system_sgpr_workgroup_info 0
		.amdhsa_system_vgpr_workitem_id 2
		.amdhsa_next_free_vgpr 256
		.amdhsa_next_free_sgpr 102
		.amdhsa_accum_offset 256
		.amdhsa_reserve_vcc 1
		.amdhsa_float_round_mode_32 0
		.amdhsa_float_round_mode_16_64 0
		.amdhsa_float_denorm_mode_32 3
		.amdhsa_float_denorm_mode_16_64 3
		.amdhsa_dx10_clamp 1
		.amdhsa_ieee_mode 1
		.amdhsa_fp16_overflow 0
		.amdhsa_tg_split 0
		.amdhsa_exception_fp_ieee_invalid_op 0
		.amdhsa_exception_fp_denorm_src 0
		.amdhsa_exception_fp_ieee_div_zero 0
		.amdhsa_exception_fp_ieee_overflow 0
		.amdhsa_exception_fp_ieee_underflow 0
		.amdhsa_exception_fp_ieee_inexact 0
		.amdhsa_exception_int_div_zero 0
	.end_amdhsa_kernel

; __global__ void __launch_bounds__(512, 2) fwd_megakernel(Args a) {
;   extern __shared__ __attribute__((aligned(16))) unsigned char lds[];
;   cg::grid_group grid = cg::this_grid();
;   const int G = gridDim.x, c = blockIdx.x, wid_s = __builtin_amdgcn_readfirstlane((int)threadIdx.x >> 6);
amdhsa.kernels:
  - .agpr_count:     0
    .args:
      - .offset:         0
        .size:           96
        .value_kind:     by_value
      - .offset:         96
        .size:           4
        .value_kind:     hidden_block_count_x
      - .offset:         100
        .size:           4
        .value_kind:     hidden_block_count_y
      - .offset:         104
        .size:           4
        .value_kind:     hidden_block_count_z
      - .offset:         108
        .size:           2
        .value_kind:     hidden_group_size_x
      - .offset:         110
        .size:           2
        .value_kind:     hidden_group_size_y
      - .offset:         112
        .size:           2
        .value_kind:     hidden_group_size_z
      - .offset:         114
        .size:           2
        .value_kind:     hidden_remainder_x
      - .offset:         116
        .size:           2
        .value_kind:     hidden_remainder_y
      - .offset:         118
        .size:           2
        .value_kind:     hidden_remainder_z
      - .offset:         136
        .size:           8
        .value_kind:     hidden_global_offset_x
      - .offset:         144
        .size:           8
        .value_kind:     hidden_global_offset_y
      - .offset:         152
        .size:           8
        .value_kind:     hidden_global_offset_z
      - .offset:         160
        .size:           2
        .value_kind:     hidden_grid_dims
      - .offset:         184
        .size:           8
        .value_kind:     hidden_multigrid_sync_arg
      - .offset:         216
        .size:           4
        .value_kind:     hidden_dynamic_lds_size
    .group_segment_fixed_size: 0
    .kernarg_segment_align: 8
    .kernarg_segment_size: 352
    .language:       OpenCL C
    .language_version:
      - 2
      - 0
    .max_flat_workgroup_size: 512
    .name:           _Z14fwd_megakernel4Args
    .private_segment_fixed_size: 0
    .sgpr_count:     108
    .sgpr_spill_count: 0
    .symbol:         _Z14fwd_megakernel4Args.kd
    .uniform_work_group_size: 1
    .uses_dynamic_stack: false
    .vgpr_count:     256
    .vgpr_spill_count: 0
    .wavefront_size: 64
